# GEMM epilogues (EpiMix PH4/PH7, EpiZ PH1): xor-16/xor-32 ds_bpermute row-sum shuffles replaced by v_permlane16_swap/v_permlane32_swap (no LDS round trips); bit-identical
# speedup vs baseline: 1.0020x; 1.0020x over previous
; __device__ __forceinline__ unsigned cvt_pk_bf16(float lo, float hi) { unsigned r; asm volatile("v_cvt_pk_bf16_f32 %0, %1, %2" : "=v"(r) : "v"(lo), "v"(hi)); return r; }
; __device__ __forceinline__ void st8(bf16_t* p, f32x4 a, f32x4 b) { u32x4 w; w.x = cvt_pk_bf16(a[0], a[1]); w.y = cvt_pk_bf16(a[2], a[3]); w.z = cvt_pk_bf16(b[0], b[1]); w.w = cvt_pk_bf16(b[2], b[3]); *(u32x4*)p = w; }
; __device__ __forceinline__ float ssq4(f32x4 a) { return (a[0] * a[0] + a[1] * a[1]) + (a[2] * a[2] + a[3] * a[3]); }
; __device__ __forceinline__ float red_fq(float p) { p += __shfl_xor(p, 16); p += __shfl_xor(p, 32); return p; }
;     __device__ __forceinline__ void operator()(const f32x4 (&acc)[2][2][4][2], const Unit& u, int wr, int wc, int fr, int fq) const {
;     ...
;                     bf16_t* p = ZQ + (size_t)row * 768 + pn * 256 + cw;
;                     st8(p, a0, a1); st8(p + HALF, b0, b1);
;                     const float pa = red_fq(ssq4(a0) + ssq4(a1)), pb = red_fq(ssq4(b0) + ssq4(b1));
;                     if (fq == 0) { SSQ[(size_t)row * 32 + pn * 8 + wc] = pa; SSQ[(size_t)row * 32 + pn * 8 + 4 + wc] = pb; }
.LBB0_214:
	s_lshl_b32 s46, s46, 3
	s_ashr_i32 s51, s44, 31
	s_mov_b32 s50, s44
	s_ashr_i32 s47, s46, 31
	s_andn2_b64 vcc, exec, s[6:7]
	s_ashr_i32 s43, s42, 31
	s_cbranch_vccnz .LBB0_218
	v_mov_b64_e32 v[124:125], s[18:19]
	v_mad_i64_i32 v[124:125], s[0:1], v146, s77, v[124:125]
	v_mul_f32_e32 v126, v153, v153
	v_mul_f32_e32 v127, v151, v151
	v_lshl_add_u64 v[124:125], s[50:51], 1, v[124:125]
	v_fmac_f32_e32 v126, v152, v152
	v_fmac_f32_e32 v127, v150, v150
	v_lshl_add_u64 v[162:163], v[144:145], 1, v[124:125]
	v_cvt_pk_bf16_f32 v124, v152, v153
	v_cvt_pk_bf16_f32 v125, v150, v151
	v_add_f32_e32 v126, v126, v127
	v_mul_f32_e32 v127, v123, v123
	v_mul_f32_e32 v150, v121, v121
	v_fmac_f32_e32 v127, v122, v122
	v_fmac_f32_e32 v150, v120, v120
	v_add_f32_e32 v127, v127, v150
	v_add_f32_e32 v150, v126, v127
	v_and_b32_e32 v127, 64, v161
	v_xor_b32_e32 v126, 16, v161
	v_add_u32_e32 v151, 64, v127
	v_cmp_lt_i32_e32 vcc, v126, v151
	s_nop 1
	v_cndmask_b32_e32 v126, v161, v126, vcc
	v_lshlrev_b32_e32 v152, 2, v126
	v_cvt_pk_bf16_f32 v126, v122, v123
	v_cvt_pk_bf16_f32 v127, v120, v121
	global_store_dwordx4 v[162:163], v[124:127], off
	v_cvt_pk_bf16_f32 v122, v116, v117
	v_mul_f32_e32 v117, v117, v117
	v_fmac_f32_e32 v117, v116, v116
	v_mul_f32_e32 v116, v119, v119
	v_fmac_f32_e32 v116, v118, v118
	v_add_f32_e32 v116, v117, v116
	v_mul_f32_e32 v117, v113, v113
	v_mul_f32_e32 v123, v115, v115
	v_fmac_f32_e32 v117, v112, v112
	v_fmac_f32_e32 v123, v114, v114
	v_add_f32_e32 v117, v117, v123
	v_add_f32_e32 v117, v116, v117
	v_mov_b32_e32 v153, v150
	v_mov_b32_e32 v123, v117
	s_nop 1
	v_permlane16_swap_b32_e32 v153, v150
	v_permlane16_swap_b32_e32 v123, v117
	v_xor_b32_e32 v121, 32, v161
	v_cmp_lt_i32_e32 vcc, v121, v151
	s_waitcnt lgkmcnt(0)
	v_add_f32_e32 v120, v150, v153
	v_cndmask_b32_e32 v116, v161, v121, vcc
	v_lshlrev_b32_e32 v121, 2, v116
	v_add_f32_e32 v117, v117, v123
	v_mov_b32_e32 v116, v120
	v_mov_b32_e32 v121, v117
	s_nop 1
	v_permlane32_swap_b32_e32 v116, v120
	v_permlane32_swap_b32_e32 v121, v117
	v_cvt_pk_bf16_f32 v123, v118, v119
	v_cvt_pk_bf16_f32 v124, v112, v113
	v_cvt_pk_bf16_f32 v125, v114, v115
	global_store_dwordx4 v[162:163], v[122:125], off offset:256
	s_and_saveexec_b64 s[0:1], s[4:5]
	s_cbranch_execz .LBB0_217
	v_lshlrev_b64 v[112:113], 7, v[146:147]
	v_lshl_add_u64 v[112:113], s[24:25], 0, v[112:113]
	v_lshl_add_u64 v[112:113], s[46:47], 2, v[112:113]
	s_waitcnt lgkmcnt(1)
	v_add_f32_e32 v115, v120, v116
	v_lshl_add_u64 v[112:113], s[42:43], 2, v[112:113]
	s_waitcnt lgkmcnt(0)
	v_add_f32_e32 v114, v117, v121
	global_store_dword v[112:113], v115, off
	global_store_dword v[112:113], v114, off offset:16

; __device__ __forceinline__ unsigned cvt_pk_bf16(float lo, float hi) { unsigned r; asm volatile("v_cvt_pk_bf16_f32 %0, %1, %2" : "=v"(r) : "v"(lo), "v"(hi)); return r; }
; __device__ __forceinline__ void st8(bf16_t* p, f32x4 a, f32x4 b) { u32x4 w; w.x = cvt_pk_bf16(a[0], a[1]); w.y = cvt_pk_bf16(a[2], a[3]); w.z = cvt_pk_bf16(b[0], b[1]); w.w = cvt_pk_bf16(b[2], b[3]); *(u32x4*)p = w; }
; __device__ __forceinline__ float ssq4(f32x4 a) { return (a[0] * a[0] + a[1] * a[1]) + (a[2] * a[2] + a[3] * a[3]); }
; __device__ __forceinline__ float red_fq(float p) { p += __shfl_xor(p, 16); p += __shfl_xor(p, 32); return p; }
;     __device__ __forceinline__ void operator()(const f32x4 (&acc)[2][2][4][2], const Unit& u, int wr, int wc, int fr, int fq) const {
;     ...
;                     bf16_t* p = ZQ + (size_t)row * 768 + pn * 256 + cw;
;                     st8(p, a0, a1); st8(p + HALF, b0, b1);
;                     const float pa = red_fq(ssq4(a0) + ssq4(a1)), pb = red_fq(ssq4(b0) + ssq4(b1));
;                     if (fq == 0) { SSQ[(size_t)row * 32 + pn * 8 + wc] = pa; SSQ[(size_t)row * 32 + pn * 8 + 4 + wc] = pb; }
.LBB0_224:
	s_andn2_b64 vcc, exec, s[0:1]
	s_cbranch_vccnz .LBB0_228
	v_mov_b64_e32 v[114:115], s[18:19]
	v_mad_i64_i32 v[114:115], s[0:1], v112, s77, v[114:115]
	v_lshl_add_u64 v[114:115], s[50:51], 1, v[114:115]
	v_lshl_add_u64 v[118:119], v[144:145], 1, v[114:115]
	v_cvt_pk_bf16_f32 v114, v108, v109
	v_mul_f32_e32 v109, v109, v109
	v_fmac_f32_e32 v109, v108, v108
	v_mul_f32_e32 v108, v111, v111
	v_cvt_pk_bf16_f32 v115, v110, v111
	v_fmac_f32_e32 v108, v110, v110
	v_mul_f32_e32 v110, v107, v107
	v_add_f32_e32 v108, v109, v108
	v_mul_f32_e32 v109, v105, v105
	v_fmac_f32_e32 v110, v106, v106
	s_waitcnt lgkmcnt(0)
	v_cvt_pk_bf16_f32 v116, v104, v105
	v_cvt_pk_bf16_f32 v117, v106, v107
	global_store_dwordx4 v[118:119], v[114:117], off
	v_cvt_pk_bf16_f32 v106, v100, v101
	v_mul_f32_e32 v101, v101, v101
	v_fmac_f32_e32 v109, v104, v104
	v_fmac_f32_e32 v101, v100, v100
	v_mul_f32_e32 v100, v103, v103
	v_add_f32_e32 v109, v109, v110
	v_and_b32_e32 v110, 64, v161
	v_fmac_f32_e32 v100, v102, v102
	v_add_f32_e32 v108, v108, v109
	v_xor_b32_e32 v109, 16, v161
	v_add_u32_e32 v110, 64, v110
	v_add_f32_e32 v100, v101, v100
	v_mul_f32_e32 v101, v97, v97
	v_mul_f32_e32 v107, v99, v99
	v_cmp_lt_i32_e32 vcc, v109, v110
	v_fmac_f32_e32 v101, v96, v96
	v_fmac_f32_e32 v107, v98, v98
	v_cndmask_b32_e32 v109, v161, v109, vcc
	v_add_f32_e32 v101, v101, v107
	v_lshlrev_b32_e32 v109, 2, v109
	v_add_f32_e32 v101, v100, v101
	v_mov_b32_e32 v111, v108
	v_mov_b32_e32 v107, v101
	s_nop 1
	v_permlane16_swap_b32_e32 v111, v108
	v_permlane16_swap_b32_e32 v107, v101
	v_xor_b32_e32 v105, 32, v161
	v_cmp_lt_i32_e32 vcc, v105, v110
	s_waitcnt lgkmcnt(1)
	v_add_f32_e32 v104, v108, v111
	v_cndmask_b32_e32 v100, v161, v105, vcc
	v_lshlrev_b32_e32 v105, 2, v100
	s_waitcnt lgkmcnt(0)
	v_add_f32_e32 v101, v101, v107
	v_mov_b32_e32 v100, v104
	v_mov_b32_e32 v105, v101
	s_nop 1
	v_permlane32_swap_b32_e32 v100, v104
	v_permlane32_swap_b32_e32 v105, v101
	v_cvt_pk_bf16_f32 v107, v102, v103
	v_cvt_pk_bf16_f32 v108, v96, v97
	v_cvt_pk_bf16_f32 v109, v98, v99
	global_store_dwordx4 v[118:119], v[106:109], off offset:256
	s_and_saveexec_b64 s[0:1], s[4:5]
	s_cbranch_execz .LBB0_227
	v_lshlrev_b64 v[96:97], 7, v[112:113]
	v_lshl_add_u64 v[96:97], s[24:25], 0, v[96:97]
	v_lshl_add_u64 v[96:97], s[46:47], 2, v[96:97]
	s_waitcnt lgkmcnt(1)
	v_add_f32_e32 v99, v104, v100
	v_lshl_add_u64 v[96:97], s[42:43], 2, v[96:97]
	s_waitcnt lgkmcnt(0)
	v_add_f32_e32 v98, v101, v105
	global_store_dword v[96:97], v99, off
	global_store_dword v[96:97], v98, off offset:16

; __device__ __forceinline__ unsigned cvt_pk_bf16(float lo, float hi) { unsigned r; asm volatile("v_cvt_pk_bf16_f32 %0, %1, %2" : "=v"(r) : "v"(lo), "v"(hi)); return r; }
; __device__ __forceinline__ void st8(bf16_t* p, f32x4 a, f32x4 b) { u32x4 w; w.x = cvt_pk_bf16(a[0], a[1]); w.y = cvt_pk_bf16(a[2], a[3]); w.z = cvt_pk_bf16(b[0], b[1]); w.w = cvt_pk_bf16(b[2], b[3]); *(u32x4*)p = w; }
; __device__ __forceinline__ float ssq4(f32x4 a) { return (a[0] * a[0] + a[1] * a[1]) + (a[2] * a[2] + a[3] * a[3]); }
; __device__ __forceinline__ float red_fq(float p) { p += __shfl_xor(p, 16); p += __shfl_xor(p, 32); return p; }
;     __device__ __forceinline__ void operator()(const f32x4 (&acc)[2][2][4][2], const Unit& u, int wr, int wc, int fr, int fq) const {
;     ...
;                     bf16_t* p = ZQ + (size_t)row * 768 + pn * 256 + cw;
;                     st8(p, a0, a1); st8(p + HALF, b0, b1);
;                     const float pa = red_fq(ssq4(a0) + ssq4(a1)), pb = red_fq(ssq4(b0) + ssq4(b1));
;                     if (fq == 0) { SSQ[(size_t)row * 32 + pn * 8 + wc] = pa; SSQ[(size_t)row * 32 + pn * 8 + 4 + wc] = pb; }
.LBB0_234:
	s_andn2_b64 vcc, exec, s[0:1]
	s_cbranch_vccnz .LBB0_238
	v_mov_b64_e32 v[98:99], s[18:19]
	v_mad_i64_i32 v[98:99], s[0:1], v96, s77, v[98:99]
	v_lshl_add_u64 v[98:99], s[50:51], 1, v[98:99]
	v_lshl_add_u64 v[102:103], v[144:145], 1, v[98:99]
	v_cvt_pk_bf16_f32 v98, v92, v93
	v_mul_f32_e32 v93, v93, v93
	v_fmac_f32_e32 v93, v92, v92
	v_mul_f32_e32 v92, v95, v95
	v_cvt_pk_bf16_f32 v99, v94, v95
	v_fmac_f32_e32 v92, v94, v94
	v_mul_f32_e32 v94, v91, v91
	v_add_f32_e32 v92, v93, v92
	v_mul_f32_e32 v93, v89, v89
	v_fmac_f32_e32 v94, v90, v90
	s_waitcnt lgkmcnt(0)
	v_cvt_pk_bf16_f32 v100, v88, v89
	v_cvt_pk_bf16_f32 v101, v90, v91
	global_store_dwordx4 v[102:103], v[98:101], off
	v_cvt_pk_bf16_f32 v90, v84, v85
	v_mul_f32_e32 v85, v85, v85
	v_fmac_f32_e32 v93, v88, v88
	v_fmac_f32_e32 v85, v84, v84
	v_mul_f32_e32 v84, v87, v87
	v_add_f32_e32 v93, v93, v94
	v_and_b32_e32 v94, 64, v161
	v_fmac_f32_e32 v84, v86, v86
	v_add_f32_e32 v92, v92, v93
	v_xor_b32_e32 v93, 16, v161
	v_add_u32_e32 v94, 64, v94
	v_add_f32_e32 v84, v85, v84
	v_mul_f32_e32 v85, v81, v81
	v_mul_f32_e32 v91, v83, v83
	v_cmp_lt_i32_e32 vcc, v93, v94
	v_fmac_f32_e32 v85, v80, v80
	v_fmac_f32_e32 v91, v82, v82
	v_cndmask_b32_e32 v93, v161, v93, vcc
	v_add_f32_e32 v85, v85, v91
	v_lshlrev_b32_e32 v93, 2, v93
	v_add_f32_e32 v85, v84, v85
	v_mov_b32_e32 v95, v92
	v_mov_b32_e32 v91, v85
	s_nop 1
	v_permlane16_swap_b32_e32 v95, v92
	v_permlane16_swap_b32_e32 v91, v85
	v_xor_b32_e32 v89, 32, v161
	v_cmp_lt_i32_e32 vcc, v89, v94
	s_waitcnt lgkmcnt(1)
	v_add_f32_e32 v88, v92, v95
	v_cndmask_b32_e32 v84, v161, v89, vcc
	v_lshlrev_b32_e32 v89, 2, v84
	s_waitcnt lgkmcnt(0)
	v_add_f32_e32 v85, v85, v91
	v_mov_b32_e32 v84, v88
	v_mov_b32_e32 v89, v85
	s_nop 1
	v_permlane32_swap_b32_e32 v84, v88
	v_permlane32_swap_b32_e32 v89, v85
	v_cvt_pk_bf16_f32 v91, v86, v87
	v_cvt_pk_bf16_f32 v92, v80, v81
	v_cvt_pk_bf16_f32 v93, v82, v83
	global_store_dwordx4 v[102:103], v[90:93], off offset:256
	s_and_saveexec_b64 s[0:1], s[4:5]
	s_cbranch_execz .LBB0_237
	v_lshlrev_b64 v[80:81], 7, v[96:97]
	v_lshl_add_u64 v[80:81], s[24:25], 0, v[80:81]
	v_lshl_add_u64 v[80:81], s[46:47], 2, v[80:81]
	s_waitcnt lgkmcnt(1)
	v_add_f32_e32 v83, v88, v84
	v_lshl_add_u64 v[80:81], s[42:43], 2, v[80:81]
	s_waitcnt lgkmcnt(0)
	v_add_f32_e32 v82, v85, v89
	global_store_dword v[80:81], v83, off
	global_store_dword v[80:81], v82, off offset:16

; __device__ __forceinline__ unsigned cvt_pk_bf16(float lo, float hi) { unsigned r; asm volatile("v_cvt_pk_bf16_f32 %0, %1, %2" : "=v"(r) : "v"(lo), "v"(hi)); return r; }
; __device__ __forceinline__ void st8(bf16_t* p, f32x4 a, f32x4 b) { u32x4 w; w.x = cvt_pk_bf16(a[0], a[1]); w.y = cvt_pk_bf16(a[2], a[3]); w.z = cvt_pk_bf16(b[0], b[1]); w.w = cvt_pk_bf16(b[2], b[3]); *(u32x4*)p = w; }
; __device__ __forceinline__ float ssq4(f32x4 a) { return (a[0] * a[0] + a[1] * a[1]) + (a[2] * a[2] + a[3] * a[3]); }
; __device__ __forceinline__ float red_fq(float p) { p += __shfl_xor(p, 16); p += __shfl_xor(p, 32); return p; }
;     __device__ __forceinline__ void operator()(const f32x4 (&acc)[2][2][4][2], const Unit& u, int wr, int wc, int fr, int fq) const {
;     ...
;                     bf16_t* p = ZQ + (size_t)row * 768 + pn * 256 + cw;
;                     st8(p, a0, a1); st8(p + HALF, b0, b1);
;                     const float pa = red_fq(ssq4(a0) + ssq4(a1)), pb = red_fq(ssq4(b0) + ssq4(b1));
;                     if (fq == 0) { SSQ[(size_t)row * 32 + pn * 8 + wc] = pa; SSQ[(size_t)row * 32 + pn * 8 + 4 + wc] = pb; }
.LBB0_244:
	s_andn2_b64 vcc, exec, s[0:1]
	s_cbranch_vccnz .LBB0_248
	v_mov_b64_e32 v[82:83], s[18:19]
	v_mad_i64_i32 v[82:83], s[0:1], v80, s77, v[82:83]
	v_lshl_add_u64 v[82:83], s[50:51], 1, v[82:83]
	v_lshl_add_u64 v[86:87], v[144:145], 1, v[82:83]
	v_cvt_pk_bf16_f32 v82, v76, v77
	v_mul_f32_e32 v77, v77, v77
	v_fmac_f32_e32 v77, v76, v76
	v_mul_f32_e32 v76, v79, v79
	v_cvt_pk_bf16_f32 v83, v78, v79
	v_fmac_f32_e32 v76, v78, v78
	v_mul_f32_e32 v78, v75, v75
	v_add_f32_e32 v76, v77, v76
	v_mul_f32_e32 v77, v73, v73
	v_fmac_f32_e32 v78, v74, v74
	s_waitcnt lgkmcnt(0)
	v_cvt_pk_bf16_f32 v84, v72, v73
	v_cvt_pk_bf16_f32 v85, v74, v75
	global_store_dwordx4 v[86:87], v[82:85], off
	v_cvt_pk_bf16_f32 v74, v68, v69
	v_mul_f32_e32 v69, v69, v69
	v_fmac_f32_e32 v77, v72, v72
	v_fmac_f32_e32 v69, v68, v68
	v_mul_f32_e32 v68, v71, v71
	v_add_f32_e32 v77, v77, v78
	v_and_b32_e32 v78, 64, v161
	v_fmac_f32_e32 v68, v70, v70
	v_add_f32_e32 v76, v76, v77
	v_xor_b32_e32 v77, 16, v161
	v_add_u32_e32 v78, 64, v78
	v_add_f32_e32 v68, v69, v68
	v_mul_f32_e32 v69, v65, v65
	v_mul_f32_e32 v75, v67, v67
	v_cmp_lt_i32_e32 vcc, v77, v78
	v_fmac_f32_e32 v69, v64, v64
	v_fmac_f32_e32 v75, v66, v66
	v_cndmask_b32_e32 v77, v161, v77, vcc
	v_add_f32_e32 v69, v69, v75
	v_lshlrev_b32_e32 v77, 2, v77
	v_add_f32_e32 v69, v68, v69
	v_mov_b32_e32 v79, v76
	v_mov_b32_e32 v75, v69
	s_nop 1
	v_permlane16_swap_b32_e32 v79, v76
	v_permlane16_swap_b32_e32 v75, v69
	v_xor_b32_e32 v73, 32, v161
	v_cmp_lt_i32_e32 vcc, v73, v78
	s_waitcnt lgkmcnt(1)
	v_add_f32_e32 v72, v76, v79
	v_cndmask_b32_e32 v68, v161, v73, vcc
	v_lshlrev_b32_e32 v73, 2, v68
	s_waitcnt lgkmcnt(0)
	v_add_f32_e32 v69, v69, v75
	v_mov_b32_e32 v68, v72
	v_mov_b32_e32 v73, v69
	s_nop 1
	v_permlane32_swap_b32_e32 v68, v72
	v_permlane32_swap_b32_e32 v73, v69
	v_cvt_pk_bf16_f32 v75, v70, v71
	v_cvt_pk_bf16_f32 v76, v64, v65
	v_cvt_pk_bf16_f32 v77, v66, v67
	global_store_dwordx4 v[86:87], v[74:77], off offset:256
	s_and_saveexec_b64 s[0:1], s[4:5]
	s_cbranch_execz .LBB0_247
	v_lshlrev_b64 v[64:65], 7, v[80:81]
	v_lshl_add_u64 v[64:65], s[24:25], 0, v[64:65]
	v_lshl_add_u64 v[64:65], s[46:47], 2, v[64:65]
	s_waitcnt lgkmcnt(1)
	v_add_f32_e32 v67, v72, v68
	v_lshl_add_u64 v[64:65], s[42:43], 2, v[64:65]
	s_waitcnt lgkmcnt(0)
	v_add_f32_e32 v66, v69, v73
	global_store_dword v[64:65], v67, off
	global_store_dword v[64:65], v66, off offset:16

; __device__ __forceinline__ unsigned cvt_pk_bf16(float lo, float hi) { unsigned r; asm volatile("v_cvt_pk_bf16_f32 %0, %1, %2" : "=v"(r) : "v"(lo), "v"(hi)); return r; }
; __device__ __forceinline__ void st8(bf16_t* p, f32x4 a, f32x4 b) { u32x4 w; w.x = cvt_pk_bf16(a[0], a[1]); w.y = cvt_pk_bf16(a[2], a[3]); w.z = cvt_pk_bf16(b[0], b[1]); w.w = cvt_pk_bf16(b[2], b[3]); *(u32x4*)p = w; }
; __device__ __forceinline__ float ssq4(f32x4 a) { return (a[0] * a[0] + a[1] * a[1]) + (a[2] * a[2] + a[3] * a[3]); }
; __device__ __forceinline__ float red_fq(float p) { p += __shfl_xor(p, 16); p += __shfl_xor(p, 32); return p; }
;     __device__ __forceinline__ void operator()(const f32x4 (&acc)[2][2][4][2], const Unit& u, int wr, int wc, int fr, int fq) const {
;     ...
;                     bf16_t* p = ZQ + (size_t)row * 768 + pn * 256 + cw;
;                     st8(p, a0, a1); st8(p + HALF, b0, b1);
;                     const float pa = red_fq(ssq4(a0) + ssq4(a1)), pb = red_fq(ssq4(b0) + ssq4(b1));
;                     if (fq == 0) { SSQ[(size_t)row * 32 + pn * 8 + wc] = pa; SSQ[(size_t)row * 32 + pn * 8 + 4 + wc] = pb; }
.LBB0_254:
	s_andn2_b64 vcc, exec, s[0:1]
	s_cbranch_vccnz .LBB0_258
	v_mov_b64_e32 v[66:67], s[18:19]
	v_mad_i64_i32 v[66:67], s[0:1], v64, s77, v[66:67]
	v_lshl_add_u64 v[66:67], s[50:51], 1, v[66:67]
	v_lshl_add_u64 v[70:71], v[144:145], 1, v[66:67]
	v_cvt_pk_bf16_f32 v66, v60, v61
	v_mul_f32_e32 v61, v61, v61
	v_fmac_f32_e32 v61, v60, v60
	v_mul_f32_e32 v60, v63, v63
	v_cvt_pk_bf16_f32 v67, v62, v63
	v_fmac_f32_e32 v60, v62, v62
	v_mul_f32_e32 v62, v59, v59
	v_add_f32_e32 v60, v61, v60
	v_mul_f32_e32 v61, v57, v57
	v_fmac_f32_e32 v62, v58, v58
	s_waitcnt lgkmcnt(0)
	v_cvt_pk_bf16_f32 v68, v56, v57
	v_cvt_pk_bf16_f32 v69, v58, v59
	global_store_dwordx4 v[70:71], v[66:69], off
	v_cvt_pk_bf16_f32 v58, v52, v53
	v_mul_f32_e32 v53, v53, v53
	v_fmac_f32_e32 v61, v56, v56
	v_fmac_f32_e32 v53, v52, v52
	v_mul_f32_e32 v52, v55, v55
	v_add_f32_e32 v61, v61, v62
	v_and_b32_e32 v62, 64, v161
	v_fmac_f32_e32 v52, v54, v54
	v_add_f32_e32 v60, v60, v61
	v_xor_b32_e32 v61, 16, v161
	v_add_u32_e32 v62, 64, v62
	v_add_f32_e32 v52, v53, v52
	v_mul_f32_e32 v53, v49, v49
	v_mul_f32_e32 v59, v51, v51
	v_cmp_lt_i32_e32 vcc, v61, v62
	v_fmac_f32_e32 v53, v48, v48
	v_fmac_f32_e32 v59, v50, v50
	v_cndmask_b32_e32 v61, v161, v61, vcc
	v_add_f32_e32 v53, v53, v59
	v_lshlrev_b32_e32 v61, 2, v61
	v_add_f32_e32 v53, v52, v53
	v_mov_b32_e32 v63, v60
	v_mov_b32_e32 v59, v53
	s_nop 1
	v_permlane16_swap_b32_e32 v63, v60
	v_permlane16_swap_b32_e32 v59, v53
	v_xor_b32_e32 v57, 32, v161
	v_cmp_lt_i32_e32 vcc, v57, v62
	s_waitcnt lgkmcnt(1)
	v_add_f32_e32 v56, v60, v63
	v_cndmask_b32_e32 v52, v161, v57, vcc
	v_lshlrev_b32_e32 v57, 2, v52
	s_waitcnt lgkmcnt(0)
	v_add_f32_e32 v53, v53, v59
	v_mov_b32_e32 v52, v56
	v_mov_b32_e32 v57, v53
	s_nop 1
	v_permlane32_swap_b32_e32 v52, v56
	v_permlane32_swap_b32_e32 v57, v53
	v_cvt_pk_bf16_f32 v59, v54, v55
	v_cvt_pk_bf16_f32 v60, v48, v49
	v_cvt_pk_bf16_f32 v61, v50, v51
	global_store_dwordx4 v[70:71], v[58:61], off offset:256
	s_and_saveexec_b64 s[0:1], s[4:5]
	s_cbranch_execz .LBB0_257
	v_lshlrev_b64 v[48:49], 7, v[64:65]
	v_lshl_add_u64 v[48:49], s[24:25], 0, v[48:49]
	v_lshl_add_u64 v[48:49], s[46:47], 2, v[48:49]
	s_waitcnt lgkmcnt(1)
	v_add_f32_e32 v51, v56, v52
	v_lshl_add_u64 v[48:49], s[42:43], 2, v[48:49]
	s_waitcnt lgkmcnt(0)
	v_add_f32_e32 v50, v53, v57
	global_store_dword v[48:49], v51, off
	global_store_dword v[48:49], v50, off offset:16

; __device__ __forceinline__ unsigned cvt_pk_bf16(float lo, float hi) { unsigned r; asm volatile("v_cvt_pk_bf16_f32 %0, %1, %2" : "=v"(r) : "v"(lo), "v"(hi)); return r; }
; __device__ __forceinline__ void st8(bf16_t* p, f32x4 a, f32x4 b) { u32x4 w; w.x = cvt_pk_bf16(a[0], a[1]); w.y = cvt_pk_bf16(a[2], a[3]); w.z = cvt_pk_bf16(b[0], b[1]); w.w = cvt_pk_bf16(b[2], b[3]); *(u32x4*)p = w; }
; __device__ __forceinline__ float ssq4(f32x4 a) { return (a[0] * a[0] + a[1] * a[1]) + (a[2] * a[2] + a[3] * a[3]); }
; __device__ __forceinline__ float red_fq(float p) { p += __shfl_xor(p, 16); p += __shfl_xor(p, 32); return p; }
;     __device__ __forceinline__ void operator()(const f32x4 (&acc)[2][2][4][2], const Unit& u, int wr, int wc, int fr, int fq) const {
;     ...
;                     bf16_t* p = ZQ + (size_t)row * 768 + pn * 256 + cw;
;                     st8(p, a0, a1); st8(p + HALF, b0, b1);
;                     const float pa = red_fq(ssq4(a0) + ssq4(a1)), pb = red_fq(ssq4(b0) + ssq4(b1));
;                     if (fq == 0) { SSQ[(size_t)row * 32 + pn * 8 + wc] = pa; SSQ[(size_t)row * 32 + pn * 8 + 4 + wc] = pb; }
.LBB0_264:
	s_andn2_b64 vcc, exec, s[0:1]
	s_cbranch_vccnz .LBB0_268
	v_mov_b64_e32 v[50:51], s[18:19]
	v_mad_i64_i32 v[50:51], s[0:1], v48, s77, v[50:51]
	v_lshl_add_u64 v[50:51], s[50:51], 1, v[50:51]
	v_lshl_add_u64 v[54:55], v[144:145], 1, v[50:51]
	v_cvt_pk_bf16_f32 v50, v44, v45
	v_mul_f32_e32 v45, v45, v45
	v_fmac_f32_e32 v45, v44, v44
	v_mul_f32_e32 v44, v47, v47
	v_cvt_pk_bf16_f32 v51, v46, v47
	v_fmac_f32_e32 v44, v46, v46
	v_mul_f32_e32 v46, v43, v43
	v_add_f32_e32 v44, v45, v44
	v_mul_f32_e32 v45, v41, v41
	v_fmac_f32_e32 v46, v42, v42
	s_waitcnt lgkmcnt(0)
	v_cvt_pk_bf16_f32 v52, v40, v41
	v_cvt_pk_bf16_f32 v53, v42, v43
	global_store_dwordx4 v[54:55], v[50:53], off
	v_cvt_pk_bf16_f32 v42, v36, v37
	v_mul_f32_e32 v37, v37, v37
	v_fmac_f32_e32 v45, v40, v40
	v_fmac_f32_e32 v37, v36, v36
	v_mul_f32_e32 v36, v39, v39
	v_add_f32_e32 v45, v45, v46
	v_and_b32_e32 v46, 64, v161
	v_fmac_f32_e32 v36, v38, v38
	v_add_f32_e32 v44, v44, v45
	v_xor_b32_e32 v45, 16, v161
	v_add_u32_e32 v46, 64, v46
	v_add_f32_e32 v36, v37, v36
	v_mul_f32_e32 v37, v33, v33
	v_mul_f32_e32 v43, v35, v35
	v_cmp_lt_i32_e32 vcc, v45, v46
	v_fmac_f32_e32 v37, v32, v32
	v_fmac_f32_e32 v43, v34, v34
	v_cndmask_b32_e32 v45, v161, v45, vcc
	v_add_f32_e32 v37, v37, v43
	v_lshlrev_b32_e32 v45, 2, v45
	v_add_f32_e32 v37, v36, v37
	v_mov_b32_e32 v47, v44
	v_mov_b32_e32 v43, v37
	s_nop 1
	v_permlane16_swap_b32_e32 v47, v44
	v_permlane16_swap_b32_e32 v43, v37
	v_xor_b32_e32 v41, 32, v161
	v_cmp_lt_i32_e32 vcc, v41, v46
	s_waitcnt lgkmcnt(1)
	v_add_f32_e32 v40, v44, v47
	v_cndmask_b32_e32 v36, v161, v41, vcc
	v_lshlrev_b32_e32 v41, 2, v36
	s_waitcnt lgkmcnt(0)
	v_add_f32_e32 v37, v37, v43
	v_mov_b32_e32 v36, v40
	v_mov_b32_e32 v41, v37
	s_nop 1
	v_permlane32_swap_b32_e32 v36, v40
	v_permlane32_swap_b32_e32 v41, v37
	v_cvt_pk_bf16_f32 v43, v38, v39
	v_cvt_pk_bf16_f32 v44, v32, v33
	v_cvt_pk_bf16_f32 v45, v34, v35
	global_store_dwordx4 v[54:55], v[42:45], off offset:256
	s_and_saveexec_b64 s[0:1], s[4:5]
	s_cbranch_execz .LBB0_267
	v_lshlrev_b64 v[32:33], 7, v[48:49]
	v_lshl_add_u64 v[32:33], s[24:25], 0, v[32:33]
	v_lshl_add_u64 v[32:33], s[46:47], 2, v[32:33]
	s_waitcnt lgkmcnt(1)
	v_add_f32_e32 v35, v40, v36
	v_lshl_add_u64 v[32:33], s[42:43], 2, v[32:33]
	s_waitcnt lgkmcnt(0)
	v_add_f32_e32 v34, v37, v41
	global_store_dword v[32:33], v35, off
	global_store_dword v[32:33], v34, off offset:16

; __device__ __forceinline__ unsigned cvt_pk_bf16(float lo, float hi) { unsigned r; asm volatile("v_cvt_pk_bf16_f32 %0, %1, %2" : "=v"(r) : "v"(lo), "v"(hi)); return r; }
; __device__ __forceinline__ void st8(bf16_t* p, f32x4 a, f32x4 b) { u32x4 w; w.x = cvt_pk_bf16(a[0], a[1]); w.y = cvt_pk_bf16(a[2], a[3]); w.z = cvt_pk_bf16(b[0], b[1]); w.w = cvt_pk_bf16(b[2], b[3]); *(u32x4*)p = w; }
; __device__ __forceinline__ float ssq4(f32x4 a) { return (a[0] * a[0] + a[1] * a[1]) + (a[2] * a[2] + a[3] * a[3]); }
; __device__ __forceinline__ float red_fq(float p) { p += __shfl_xor(p, 16); p += __shfl_xor(p, 32); return p; }
;     __device__ __forceinline__ void operator()(const f32x4 (&acc)[2][2][4][2], const Unit& u, int wr, int wc, int fr, int fq) const {
;     ...
;                     bf16_t* p = ZQ + (size_t)row * 768 + pn * 256 + cw;
;                     st8(p, a0, a1); st8(p + HALF, b0, b1);
;                     const float pa = red_fq(ssq4(a0) + ssq4(a1)), pb = red_fq(ssq4(b0) + ssq4(b1));
;                     if (fq == 0) { SSQ[(size_t)row * 32 + pn * 8 + wc] = pa; SSQ[(size_t)row * 32 + pn * 8 + 4 + wc] = pb; }
.LBB0_274:
	s_andn2_b64 vcc, exec, s[0:1]
	s_cbranch_vccnz .LBB0_278
	v_mov_b64_e32 v[34:35], s[18:19]
	v_mad_i64_i32 v[34:35], s[0:1], v32, s77, v[34:35]
	v_lshl_add_u64 v[34:35], s[50:51], 1, v[34:35]
	v_lshl_add_u64 v[38:39], v[144:145], 1, v[34:35]
	v_cvt_pk_bf16_f32 v34, v28, v29
	v_mul_f32_e32 v29, v29, v29
	v_fmac_f32_e32 v29, v28, v28
	v_mul_f32_e32 v28, v31, v31
	v_cvt_pk_bf16_f32 v35, v30, v31
	v_fmac_f32_e32 v28, v30, v30
	v_mul_f32_e32 v30, v27, v27
	v_add_f32_e32 v28, v29, v28
	v_mul_f32_e32 v29, v25, v25
	v_fmac_f32_e32 v30, v26, v26
	s_waitcnt lgkmcnt(0)
	v_cvt_pk_bf16_f32 v36, v24, v25
	v_cvt_pk_bf16_f32 v37, v26, v27
	global_store_dwordx4 v[38:39], v[34:37], off
	v_cvt_pk_bf16_f32 v26, v20, v21
	v_mul_f32_e32 v21, v21, v21
	v_fmac_f32_e32 v29, v24, v24
	v_fmac_f32_e32 v21, v20, v20
	v_mul_f32_e32 v20, v23, v23
	v_add_f32_e32 v29, v29, v30
	v_and_b32_e32 v30, 64, v161
	v_fmac_f32_e32 v20, v22, v22
	v_add_f32_e32 v28, v28, v29
	v_xor_b32_e32 v29, 16, v161
	v_add_u32_e32 v30, 64, v30
	v_add_f32_e32 v20, v21, v20
	v_mul_f32_e32 v21, v17, v17
	v_mul_f32_e32 v27, v19, v19
	v_cmp_lt_i32_e32 vcc, v29, v30
	v_fmac_f32_e32 v21, v16, v16
	v_fmac_f32_e32 v27, v18, v18
	v_cndmask_b32_e32 v29, v161, v29, vcc
	v_add_f32_e32 v21, v21, v27
	v_lshlrev_b32_e32 v29, 2, v29
	v_add_f32_e32 v21, v20, v21
	v_mov_b32_e32 v31, v28
	v_mov_b32_e32 v27, v21
	s_nop 1
	v_permlane16_swap_b32_e32 v31, v28
	v_permlane16_swap_b32_e32 v27, v21
	v_xor_b32_e32 v25, 32, v161
	v_cmp_lt_i32_e32 vcc, v25, v30
	s_waitcnt lgkmcnt(1)
	v_add_f32_e32 v24, v28, v31
	v_cndmask_b32_e32 v20, v161, v25, vcc
	v_lshlrev_b32_e32 v25, 2, v20
	s_waitcnt lgkmcnt(0)
	v_add_f32_e32 v21, v21, v27
	v_mov_b32_e32 v20, v24
	v_mov_b32_e32 v25, v21
	s_nop 1
	v_permlane32_swap_b32_e32 v20, v24
	v_permlane32_swap_b32_e32 v25, v21
	v_cvt_pk_bf16_f32 v27, v22, v23
	v_cvt_pk_bf16_f32 v28, v16, v17
	v_cvt_pk_bf16_f32 v29, v18, v19
	global_store_dwordx4 v[38:39], v[26:29], off offset:256
	s_and_saveexec_b64 s[0:1], s[4:5]
	s_cbranch_execz .LBB0_277
	v_lshlrev_b64 v[16:17], 7, v[32:33]
	v_lshl_add_u64 v[16:17], s[24:25], 0, v[16:17]
	v_lshl_add_u64 v[16:17], s[46:47], 2, v[16:17]
	s_waitcnt lgkmcnt(1)
	v_add_f32_e32 v19, v24, v20
	v_lshl_add_u64 v[16:17], s[42:43], 2, v[16:17]
	s_waitcnt lgkmcnt(0)
	v_add_f32_e32 v18, v21, v25
	global_store_dword v[16:17], v19, off
	global_store_dword v[16:17], v18, off offset:16

; __device__ __forceinline__ unsigned cvt_pk_bf16(float lo, float hi) { unsigned r; asm volatile("v_cvt_pk_bf16_f32 %0, %1, %2" : "=v"(r) : "v"(lo), "v"(hi)); return r; }
; __device__ __forceinline__ void st8(bf16_t* p, f32x4 a, f32x4 b) { u32x4 w; w.x = cvt_pk_bf16(a[0], a[1]); w.y = cvt_pk_bf16(a[2], a[3]); w.z = cvt_pk_bf16(b[0], b[1]); w.w = cvt_pk_bf16(b[2], b[3]); *(u32x4*)p = w; }
; __device__ __forceinline__ float ssq4(f32x4 a) { return (a[0] * a[0] + a[1] * a[1]) + (a[2] * a[2] + a[3] * a[3]); }
; __device__ __forceinline__ float red_fq(float p) { p += __shfl_xor(p, 16); p += __shfl_xor(p, 32); return p; }
;     __device__ __forceinline__ void operator()(const f32x4 (&acc)[2][2][4][2], const Unit& u, int wr, int wc, int fr, int fq) const {
;     ...
;                 const int row = row0 + ai * HALF + m * 16;
;                 const float s = rsqrtf(ssqX[row] * (1.0f / 1024.0f) + EPS);
;                 const f32x4 a0 = acc[ai][0][m][0] * s, a1 = acc[ai][0][m][1] * s, b0 = acc[ai][1][m][0] * s, b1 = acc[ai][1][m][1] * s;
;                 if (pn < 3) {
;                     bf16_t* p = ZQ + (size_t)row * 768 + pn * 256 + cw;
;                     st8(p, a0, a1); st8(p + HALF, b0, b1);
;                     const float pa = red_fq(ssq4(a0) + ssq4(a1)), pb = red_fq(ssq4(b0) + ssq4(b1));
;                     if (fq == 0) { SSQ[(size_t)row * 32 + pn * 8 + wc] = pa; SSQ[(size_t)row * 32 + pn * 8 + 4 + wc] = pb; }
.LBB0_284:
	s_andn2_b64 vcc, exec, s[0:1]
	s_cbranch_vccnz .LBB0_288
	v_mov_b64_e32 v[18:19], s[18:19]
	v_mad_i64_i32 v[18:19], s[0:1], v16, s77, v[18:19]
	v_lshl_add_u64 v[18:19], s[50:51], 1, v[18:19]
	v_lshl_add_u64 v[22:23], v[144:145], 1, v[18:19]
	v_cvt_pk_bf16_f32 v18, v12, v13
	v_mul_f32_e32 v13, v13, v13
	v_fmac_f32_e32 v13, v12, v12
	v_mul_f32_e32 v12, v15, v15
	v_cvt_pk_bf16_f32 v19, v14, v15
	v_fmac_f32_e32 v12, v14, v14
	v_mul_f32_e32 v14, v11, v11
	v_add_f32_e32 v12, v13, v12
	v_mul_f32_e32 v13, v9, v9
	v_fmac_f32_e32 v14, v10, v10
	s_waitcnt lgkmcnt(0)
	v_cvt_pk_bf16_f32 v20, v8, v9
	v_cvt_pk_bf16_f32 v21, v10, v11
	global_store_dwordx4 v[22:23], v[18:21], off
	v_cvt_pk_bf16_f32 v10, v4, v5
	v_mul_f32_e32 v5, v5, v5
	v_fmac_f32_e32 v13, v8, v8
	v_fmac_f32_e32 v5, v4, v4
	v_mul_f32_e32 v4, v7, v7
	v_add_f32_e32 v13, v13, v14
	v_and_b32_e32 v14, 64, v161
	v_fmac_f32_e32 v4, v6, v6
	v_add_f32_e32 v12, v12, v13
	v_xor_b32_e32 v13, 16, v161
	v_add_u32_e32 v14, 64, v14
	v_add_f32_e32 v4, v5, v4
	v_mul_f32_e32 v5, v1, v1
	v_mul_f32_e32 v11, v3, v3
	v_cmp_lt_i32_e32 vcc, v13, v14
	v_fmac_f32_e32 v5, v0, v0
	v_fmac_f32_e32 v11, v2, v2
	v_cndmask_b32_e32 v13, v161, v13, vcc
	v_add_f32_e32 v5, v5, v11
	v_lshlrev_b32_e32 v13, 2, v13
	v_add_f32_e32 v5, v4, v5
	v_mov_b32_e32 v15, v12
	v_mov_b32_e32 v11, v5
	s_nop 1
	v_permlane16_swap_b32_e32 v15, v12
	v_permlane16_swap_b32_e32 v11, v5
	v_xor_b32_e32 v9, 32, v161
	v_cmp_lt_i32_e32 vcc, v9, v14
	s_waitcnt lgkmcnt(1)
	v_add_f32_e32 v8, v12, v15
	v_cndmask_b32_e32 v4, v161, v9, vcc
	v_lshlrev_b32_e32 v9, 2, v4
	s_waitcnt lgkmcnt(0)
	v_add_f32_e32 v5, v5, v11
	v_mov_b32_e32 v4, v8
	v_mov_b32_e32 v9, v5
	s_nop 1
	v_permlane32_swap_b32_e32 v4, v8
	v_permlane32_swap_b32_e32 v9, v5
	v_cvt_pk_bf16_f32 v11, v6, v7
	v_cvt_pk_bf16_f32 v12, v0, v1
	v_cvt_pk_bf16_f32 v13, v2, v3
	global_store_dwordx4 v[22:23], v[10:13], off offset:256
	s_and_saveexec_b64 s[0:1], s[4:5]
	s_cbranch_execz .LBB0_287
	v_lshlrev_b64 v[0:1], 7, v[16:17]
	v_lshl_add_u64 v[0:1], s[24:25], 0, v[0:1]
	v_lshl_add_u64 v[0:1], s[46:47], 2, v[0:1]
	s_waitcnt lgkmcnt(1)
	v_add_f32_e32 v3, v8, v4
	v_lshl_add_u64 v[0:1], s[42:43], 2, v[0:1]
	s_waitcnt lgkmcnt(0)
	v_add_f32_e32 v2, v5, v9
	global_store_dword v[0:1], v3, off
	global_store_dword v[0:1], v2, off offset:16

; __device__ __forceinline__ unsigned cvt_pk_bf16(float lo, float hi) { unsigned r; asm volatile("v_cvt_pk_bf16_f32 %0, %1, %2" : "=v"(r) : "v"(lo), "v"(hi)); return r; }
; __device__ __forceinline__ void st8(bf16_t* p, f32x4 a, f32x4 b) { u32x4 w; w.x = cvt_pk_bf16(a[0], a[1]); w.y = cvt_pk_bf16(a[2], a[3]); w.z = cvt_pk_bf16(b[0], b[1]); w.w = cvt_pk_bf16(b[2], b[3]); *(u32x4*)p = w; }
; __device__ __forceinline__ float ssq4(f32x4 a) { return (a[0] * a[0] + a[1] * a[1]) + (a[2] * a[2] + a[3] * a[3]); }
; __device__ __forceinline__ float red_fq(float p) { p += __shfl_xor(p, 16); p += __shfl_xor(p, 32); return p; }
;     __device__ __forceinline__ void operator()(const f32x4 (&acc)[2][2][4][2], const Unit& u, int wr, int wc, int fr, int fq) const {
;     ...
;                 const int row = row0 + ai * HALF + m * 16;
;                 const f32x4 a0 = acc[ai][0][m][0], a1 = acc[ai][0][m][1], b0 = acc[ai][1][m][0], b1 = acc[ai][1][m][1];
;                 bf16_t* p = OUT + (size_t)row * 1024 + pn * 256 + cw;
;                 st8(p, a0, a1); st8(p + HALF, b0, b1);
;                 const float pa = red_fq(ssq4(a0) + ssq4(a1)), pb = red_fq(ssq4(b0) + ssq4(b1));
;                 if (fq == 0) { SSQ[(size_t)row * 32 + pn * 8 + wc] = pa; SSQ[(size_t)row * 32 + pn * 8 + 4 + wc] = pb; }
.LBB0_675:
	v_mov_b32_e32 v145, v148
	v_mov_b32_e32 v147, v149
	s_mov_b32 s6, s50
	s_mov_b32 s1, s41
	s_lshl_b32 s0, s0, 8
	s_lshl_b32 s1, s1, 6
	s_add_i32 s1, s1, s0
	v_add_u32_e32 v146, s1, v145
	v_lshlrev_b32_e32 v144, 3, v147
	v_cmp_eq_u32_e32 vcc, 0, v147
	v_ashrrev_i32_e32 v147, 31, v146
	s_lshl_b32 s34, s59, 8
	v_lshlrev_b64 v[156:157], 11, v[146:147]
	v_lshl_add_u32 v144, s6, 5, v144
	s_ashr_i32 s35, s34, 31
	v_lshl_add_u64 v[156:157], s[10:11], 0, v[156:157]
	v_ashrrev_i32_e32 v145, 31, v144
	v_lshl_add_u64 v[156:157], s[34:35], 1, v[156:157]
	v_lshl_add_u64 v[160:161], v[144:145], 1, v[156:157]
	v_cvt_pk_bf16_f32 v156, v124, v125
	v_mul_f32_e32 v125, v125, v125
	v_fmac_f32_e32 v125, v124, v124
	v_mul_f32_e32 v124, v127, v127
	v_fmac_f32_e32 v124, v126, v126
	v_cvt_pk_bf16_f32 v157, v126, v127
	v_add_f32_e32 v124, v125, v124
	v_mul_f32_e32 v125, v121, v121
	v_mul_f32_e32 v126, v123, v123
	v_cvt_pk_bf16_f32 v158, v120, v121
	v_cvt_pk_bf16_f32 v159, v122, v123
	global_store_dwordx4 v[160:161], v[156:159], off
	v_fmac_f32_e32 v125, v120, v120
	v_fmac_f32_e32 v126, v122, v122
	v_cvt_pk_bf16_f32 v156, v116, v117
	v_mul_f32_e32 v117, v117, v117
	v_fmac_f32_e32 v117, v116, v116
	v_mul_f32_e32 v116, v119, v119
	v_add_f32_e32 v125, v125, v126
	v_and_b32_e32 v126, 64, v154
	v_fmac_f32_e32 v116, v118, v118
	v_add_f32_e32 v125, v125, v124
	v_xor_b32_e32 v124, 16, v154
	v_add_u32_e32 v126, 64, v126
	v_add_f32_e32 v116, v117, v116
	v_mul_f32_e32 v117, v113, v113
	v_mul_f32_e32 v122, v115, v115
	v_cmp_lt_i32_e64 s[0:1], v124, v126
	v_fmac_f32_e32 v117, v112, v112
	v_fmac_f32_e32 v122, v114, v114
	v_cndmask_b32_e64 v124, v154, v124, s[0:1]
	v_add_f32_e32 v117, v117, v122
	v_lshlrev_b32_e32 v124, 2, v124
	v_add_f32_e32 v122, v117, v116
	v_mov_b32_e32 v127, v125
	v_mov_b32_e32 v123, v122
	s_nop 1
	v_permlane16_swap_b32_e32 v127, v125
	v_permlane16_swap_b32_e32 v123, v122
	v_xor_b32_e32 v121, 32, v154
	v_cmp_lt_i32_e64 s[0:1], v121, v126
	s_lshl_b32 s30, s59, 3
	s_waitcnt lgkmcnt(0)
	v_add_f32_e32 v120, v125, v127
	v_cndmask_b32_e64 v116, v154, v121, s[0:1]
	v_lshlrev_b32_e32 v116, 2, v116
	v_add_f32_e32 v121, v122, v123
	v_mov_b32_e32 v117, v120
	v_mov_b32_e32 v122, v121
	s_nop 1
	v_permlane32_swap_b32_e32 v117, v120
	v_permlane32_swap_b32_e32 v122, v121
	s_ashr_i32 s31, s30, 31
	s_ashr_i32 s7, s6, 31
	v_cvt_pk_bf16_f32 v157, v118, v119
	v_cvt_pk_bf16_f32 v158, v112, v113
	v_cvt_pk_bf16_f32 v159, v114, v115
	global_store_dwordx4 v[160:161], v[156:159], off offset:256
	s_and_saveexec_b64 s[0:1], vcc
	s_cbranch_execz .LBB0_677
	v_lshlrev_b64 v[112:113], 7, v[146:147]
	v_lshl_add_u64 v[112:113], s[18:19], 0, v[112:113]
	v_lshl_add_u64 v[112:113], s[30:31], 2, v[112:113]
	s_waitcnt lgkmcnt(0)
	v_add_f32_e32 v115, v120, v117
	v_lshl_add_u64 v[112:113], s[6:7], 2, v[112:113]
	v_add_f32_e32 v114, v121, v122
	global_store_dword v[112:113], v115, off
	global_store_dword v[112:113], v114, off offset:16
.LBB0_677:
	s_or_b64 exec, exec, s[0:1]
	v_cvt_pk_bf16_f32 v118, v108, v109
	v_cvt_pk_bf16_f32 v119, v110, v111
	v_cvt_pk_bf16_f32 v120, v104, v105
	v_mul_f32_e32 v109, v109, v109
	v_mul_f32_e32 v105, v105, v105
	v_fmac_f32_e32 v109, v108, v108
	v_mul_f32_e32 v108, v111, v111
	v_fmac_f32_e32 v105, v104, v104
	v_mul_f32_e32 v104, v107, v107
	v_cvt_pk_bf16_f32 v121, v106, v107
	v_fmac_f32_e32 v108, v110, v110
	v_fmac_f32_e32 v104, v106, v106
	v_mul_f32_e32 v106, v101, v101
	v_mul_f32_e32 v107, v103, v103
	v_add_f32_e32 v108, v109, v108
	v_add_f32_e32 v104, v105, v104
	v_fmac_f32_e32 v106, v100, v100
	v_fmac_f32_e32 v107, v102, v102
	v_add_f32_e32 v104, v104, v108
	v_add_f32_e32 v106, v106, v107
	v_mul_f32_e32 v107, v97, v97
	v_mul_f32_e32 v108, v99, v99
	v_fmac_f32_e32 v107, v96, v96
	v_fmac_f32_e32 v108, v98, v98
	v_add_f32_e32 v107, v107, v108
	v_add_u32_e32 v112, 16, v146
	v_add_f32_e32 v107, v107, v106
	v_ashrrev_i32_e32 v113, 31, v112
	v_mov_b32_e32 v105, v104
	v_mov_b32_e32 v108, v107
	s_nop 1
	v_permlane16_swap_b32_e32 v105, v104
	v_permlane16_swap_b32_e32 v108, v107
	v_lshlrev_b64 v[114:115], 11, v[112:113]
	v_lshl_add_u64 v[114:115], s[10:11], 0, v[114:115]
	v_lshl_add_u64 v[114:115], s[34:35], 1, v[114:115]
	v_lshl_add_u64 v[114:115], v[144:145], 1, v[114:115]
	global_store_dwordx4 v[114:115], v[118:121], off
	v_cvt_pk_bf16_f32 v106, v100, v101
	s_waitcnt lgkmcnt(0)
	v_add_f32_e32 v100, v104, v105
	v_add_f32_e32 v104, v107, v108
	v_mov_b32_e32 v101, v100
	v_mov_b32_e32 v105, v104
	s_nop 1
	v_permlane32_swap_b32_e32 v101, v100
	v_permlane32_swap_b32_e32 v105, v104
	v_cvt_pk_bf16_f32 v107, v102, v103
	v_cvt_pk_bf16_f32 v108, v96, v97
	v_cvt_pk_bf16_f32 v109, v98, v99
	global_store_dwordx4 v[114:115], v[106:109], off offset:256
	s_and_saveexec_b64 s[0:1], vcc
	s_cbranch_execz .LBB0_679
	v_lshlrev_b64 v[96:97], 7, v[112:113]
	v_lshl_add_u64 v[96:97], s[18:19], 0, v[96:97]
	v_lshl_add_u64 v[96:97], s[30:31], 2, v[96:97]
	s_waitcnt lgkmcnt(0)
	v_add_f32_e32 v99, v100, v101
	v_lshl_add_u64 v[96:97], s[6:7], 2, v[96:97]
	v_add_f32_e32 v98, v104, v105
	global_store_dword v[96:97], v99, off
	global_store_dword v[96:97], v98, off offset:16
; __device__ __forceinline__ unsigned cvt_pk_bf16(float lo, float hi) { unsigned r; asm volatile("v_cvt_pk_bf16_f32 %0, %1, %2" : "=v"(r) : "v"(lo), "v"(hi)); return r; }
; __device__ __forceinline__ void st8(bf16_t* p, f32x4 a, f32x4 b) { u32x4 w; w.x = cvt_pk_bf16(a[0], a[1]); w.y = cvt_pk_bf16(a[2], a[3]); w.z = cvt_pk_bf16(b[0], b[1]); w.w = cvt_pk_bf16(b[2], b[3]); *(u32x4*)p = w; }
; __device__ __forceinline__ float ssq4(f32x4 a) { return (a[0] * a[0] + a[1] * a[1]) + (a[2] * a[2] + a[3] * a[3]); }
; __device__ __forceinline__ float red_fq(float p) { p += __shfl_xor(p, 16); p += __shfl_xor(p, 32); return p; }
;     __device__ __forceinline__ void operator()(const f32x4 (&acc)[2][2][4][2], const Unit& u, int wr, int wc, int fr, int fq) const {
;     ...
;                 const int row = row0 + ai * HALF + m * 16;
;                 const f32x4 a0 = acc[ai][0][m][0], a1 = acc[ai][0][m][1], b0 = acc[ai][1][m][0], b1 = acc[ai][1][m][1];
;                 bf16_t* p = OUT + (size_t)row * 1024 + pn * 256 + cw;
;                 st8(p, a0, a1); st8(p + HALF, b0, b1);
;                 const float pa = red_fq(ssq4(a0) + ssq4(a1)), pb = red_fq(ssq4(b0) + ssq4(b1));
;                 if (fq == 0) { SSQ[(size_t)row * 32 + pn * 8 + wc] = pa; SSQ[(size_t)row * 32 + pn * 8 + 4 + wc] = pb; }
.LBB0_679:
	s_or_b64 exec, exec, s[0:1]
	v_add_u32_e32 v96, 32, v146
	v_ashrrev_i32_e32 v97, 31, v96
	v_lshlrev_b64 v[98:99], 11, v[96:97]
	v_lshl_add_u64 v[98:99], s[10:11], 0, v[98:99]
	v_lshl_add_u64 v[98:99], s[34:35], 1, v[98:99]
	v_lshl_add_u64 v[102:103], v[144:145], 1, v[98:99]
	v_cvt_pk_bf16_f32 v98, v92, v93
	v_cvt_pk_bf16_f32 v99, v94, v95
	v_cvt_pk_bf16_f32 v100, v88, v89
	v_mul_f32_e32 v93, v93, v93
	v_mul_f32_e32 v89, v89, v89
	v_fmac_f32_e32 v93, v92, v92
	v_mul_f32_e32 v92, v95, v95
	v_fmac_f32_e32 v89, v88, v88
	v_mul_f32_e32 v88, v91, v91
	s_waitcnt lgkmcnt(0)
	v_cvt_pk_bf16_f32 v101, v90, v91
	v_fmac_f32_e32 v92, v94, v94
	v_fmac_f32_e32 v88, v90, v90
	v_mul_f32_e32 v90, v85, v85
	v_mul_f32_e32 v91, v87, v87
	v_add_f32_e32 v92, v93, v92
	v_add_f32_e32 v88, v89, v88
	v_fmac_f32_e32 v90, v84, v84
	v_fmac_f32_e32 v91, v86, v86
	v_add_f32_e32 v88, v88, v92
	v_add_f32_e32 v90, v90, v91
	v_mul_f32_e32 v91, v81, v81
	v_mul_f32_e32 v92, v83, v83
	v_fmac_f32_e32 v91, v80, v80
	v_fmac_f32_e32 v92, v82, v82
	v_add_f32_e32 v91, v91, v92
	v_add_f32_e32 v91, v91, v90
	v_mov_b32_e32 v89, v88
	v_mov_b32_e32 v92, v91
	s_nop 1
	v_permlane16_swap_b32_e32 v89, v88
	v_permlane16_swap_b32_e32 v92, v91
	global_store_dwordx4 v[102:103], v[98:101], off
	v_cvt_pk_bf16_f32 v90, v84, v85
	s_waitcnt lgkmcnt(0)
	v_add_f32_e32 v84, v88, v89
	v_add_f32_e32 v88, v91, v92
	v_mov_b32_e32 v85, v84
	v_mov_b32_e32 v89, v88
	s_nop 1
	v_permlane32_swap_b32_e32 v85, v84
	v_permlane32_swap_b32_e32 v89, v88
	v_cvt_pk_bf16_f32 v91, v86, v87
	v_cvt_pk_bf16_f32 v92, v80, v81
	v_cvt_pk_bf16_f32 v93, v82, v83
	global_store_dwordx4 v[102:103], v[90:93], off offset:256
	s_and_saveexec_b64 s[0:1], vcc
	s_cbranch_execz .LBB0_681
	v_lshlrev_b64 v[80:81], 7, v[96:97]
	v_lshl_add_u64 v[80:81], s[18:19], 0, v[80:81]
	v_lshl_add_u64 v[80:81], s[30:31], 2, v[80:81]
	s_waitcnt lgkmcnt(0)
	v_add_f32_e32 v83, v84, v85
	v_lshl_add_u64 v[80:81], s[6:7], 2, v[80:81]
	v_add_f32_e32 v82, v88, v89
	global_store_dword v[80:81], v83, off
	global_store_dword v[80:81], v82, off offset:16
.LBB0_681:
	s_or_b64 exec, exec, s[0:1]
	v_add_u32_e32 v80, 48, v146
	v_ashrrev_i32_e32 v81, 31, v80
	v_lshlrev_b64 v[82:83], 11, v[80:81]
	v_lshl_add_u64 v[82:83], s[10:11], 0, v[82:83]
	v_lshl_add_u64 v[82:83], s[34:35], 1, v[82:83]
	v_lshl_add_u64 v[86:87], v[144:145], 1, v[82:83]
	v_cvt_pk_bf16_f32 v82, v76, v77
	v_cvt_pk_bf16_f32 v83, v78, v79
	v_cvt_pk_bf16_f32 v84, v72, v73
	v_mul_f32_e32 v77, v77, v77
	v_mul_f32_e32 v73, v73, v73
	v_fmac_f32_e32 v77, v76, v76
	v_mul_f32_e32 v76, v79, v79
	v_fmac_f32_e32 v73, v72, v72
	v_mul_f32_e32 v72, v75, v75
	s_waitcnt lgkmcnt(0)
	v_cvt_pk_bf16_f32 v85, v74, v75
	v_fmac_f32_e32 v76, v78, v78
	v_fmac_f32_e32 v72, v74, v74
	v_mul_f32_e32 v74, v69, v69
	v_mul_f32_e32 v75, v71, v71
	v_add_f32_e32 v76, v77, v76
	v_add_f32_e32 v72, v73, v72
	v_fmac_f32_e32 v74, v68, v68
	v_fmac_f32_e32 v75, v70, v70
	v_add_f32_e32 v72, v72, v76
	v_add_f32_e32 v74, v74, v75
	v_mul_f32_e32 v75, v65, v65
	v_mul_f32_e32 v76, v67, v67
	v_fmac_f32_e32 v75, v64, v64
	v_fmac_f32_e32 v76, v66, v66
	v_add_f32_e32 v75, v75, v76
	v_add_f32_e32 v75, v75, v74
	v_mov_b32_e32 v73, v72
	v_mov_b32_e32 v76, v75
	s_nop 1
	v_permlane16_swap_b32_e32 v73, v72
	v_permlane16_swap_b32_e32 v76, v75
	global_store_dwordx4 v[86:87], v[82:85], off
	v_cvt_pk_bf16_f32 v74, v68, v69
	s_waitcnt lgkmcnt(0)
	v_add_f32_e32 v68, v72, v73
	v_add_f32_e32 v72, v75, v76
	v_mov_b32_e32 v69, v68
	v_mov_b32_e32 v73, v72
	s_nop 1
	v_permlane32_swap_b32_e32 v69, v68
	v_permlane32_swap_b32_e32 v73, v72
	v_cvt_pk_bf16_f32 v75, v70, v71
	v_cvt_pk_bf16_f32 v76, v64, v65
	v_cvt_pk_bf16_f32 v77, v66, v67
	global_store_dwordx4 v[86:87], v[74:77], off offset:256
	s_and_saveexec_b64 s[0:1], vcc
	s_cbranch_execz .LBB0_683
	v_lshlrev_b64 v[64:65], 7, v[80:81]
	v_lshl_add_u64 v[64:65], s[18:19], 0, v[64:65]
	v_lshl_add_u64 v[64:65], s[30:31], 2, v[64:65]
	s_waitcnt lgkmcnt(0)
	v_add_f32_e32 v67, v68, v69
	v_lshl_add_u64 v[64:65], s[6:7], 2, v[64:65]
	v_add_f32_e32 v66, v72, v73
	global_store_dword v[64:65], v67, off
	global_store_dword v[64:65], v66, off offset:16
.LBB0_683:
	s_or_b64 exec, exec, s[0:1]
	v_add_u32_e32 v64, 0x80, v146
	v_ashrrev_i32_e32 v65, 31, v64
	v_lshlrev_b64 v[66:67], 11, v[64:65]
	v_lshl_add_u64 v[66:67], s[10:11], 0, v[66:67]
	v_lshl_add_u64 v[66:67], s[34:35], 1, v[66:67]
	v_lshl_add_u64 v[70:71], v[144:145], 1, v[66:67]
	v_cvt_pk_bf16_f32 v66, v60, v61
	v_cvt_pk_bf16_f32 v67, v62, v63
	v_cvt_pk_bf16_f32 v68, v56, v57
	v_mul_f32_e32 v61, v61, v61
	v_mul_f32_e32 v57, v57, v57
	v_fmac_f32_e32 v61, v60, v60
	v_mul_f32_e32 v60, v63, v63
	v_fmac_f32_e32 v57, v56, v56
	v_mul_f32_e32 v56, v59, v59
	s_waitcnt lgkmcnt(0)
	v_cvt_pk_bf16_f32 v69, v58, v59
	v_fmac_f32_e32 v60, v62, v62
	v_fmac_f32_e32 v56, v58, v58
	v_mul_f32_e32 v58, v53, v53
	v_mul_f32_e32 v59, v55, v55
	v_add_f32_e32 v60, v61, v60
	v_add_f32_e32 v56, v57, v56
	v_fmac_f32_e32 v58, v52, v52
	v_fmac_f32_e32 v59, v54, v54
	v_add_f32_e32 v56, v56, v60
	v_add_f32_e32 v58, v58, v59
	v_mul_f32_e32 v59, v49, v49
	v_mul_f32_e32 v60, v51, v51
	v_fmac_f32_e32 v59, v48, v48
	v_fmac_f32_e32 v60, v50, v50
	v_add_f32_e32 v59, v59, v60
	v_add_f32_e32 v59, v59, v58
	v_mov_b32_e32 v57, v56
	v_mov_b32_e32 v60, v59
	s_nop 1
	v_permlane16_swap_b32_e32 v57, v56
	v_permlane16_swap_b32_e32 v60, v59
	global_store_dwordx4 v[70:71], v[66:69], off
	v_cvt_pk_bf16_f32 v58, v52, v53
	s_waitcnt lgkmcnt(0)
	v_add_f32_e32 v52, v56, v57
	v_add_f32_e32 v56, v59, v60
	v_mov_b32_e32 v53, v52
	v_mov_b32_e32 v57, v56
	s_nop 1
	v_permlane32_swap_b32_e32 v53, v52
	v_permlane32_swap_b32_e32 v57, v56
	v_cvt_pk_bf16_f32 v59, v54, v55
	v_cvt_pk_bf16_f32 v60, v48, v49
	v_cvt_pk_bf16_f32 v61, v50, v51
	global_store_dwordx4 v[70:71], v[58:61], off offset:256
	s_and_saveexec_b64 s[0:1], vcc
	s_cbranch_execz .LBB0_685
	v_lshlrev_b64 v[48:49], 7, v[64:65]
	v_lshl_add_u64 v[48:49], s[18:19], 0, v[48:49]
	v_lshl_add_u64 v[48:49], s[30:31], 2, v[48:49]
	s_waitcnt lgkmcnt(0)
	v_add_f32_e32 v51, v52, v53
	v_lshl_add_u64 v[48:49], s[6:7], 2, v[48:49]
	v_add_f32_e32 v50, v56, v57
	global_store_dword v[48:49], v51, off
	global_store_dword v[48:49], v50, off offset:16
; __device__ __forceinline__ unsigned cvt_pk_bf16(float lo, float hi) { unsigned r; asm volatile("v_cvt_pk_bf16_f32 %0, %1, %2" : "=v"(r) : "v"(lo), "v"(hi)); return r; }
; __device__ __forceinline__ void st8(bf16_t* p, f32x4 a, f32x4 b) { u32x4 w; w.x = cvt_pk_bf16(a[0], a[1]); w.y = cvt_pk_bf16(a[2], a[3]); w.z = cvt_pk_bf16(b[0], b[1]); w.w = cvt_pk_bf16(b[2], b[3]); *(u32x4*)p = w; }
; __device__ __forceinline__ float ssq4(f32x4 a) { return (a[0] * a[0] + a[1] * a[1]) + (a[2] * a[2] + a[3] * a[3]); }
; __device__ __forceinline__ float red_fq(float p) { p += __shfl_xor(p, 16); p += __shfl_xor(p, 32); return p; }
;     __device__ __forceinline__ void operator()(const f32x4 (&acc)[2][2][4][2], const Unit& u, int wr, int wc, int fr, int fq) const {
;     ...
;                 const int row = row0 + ai * HALF + m * 16;
;                 const f32x4 a0 = acc[ai][0][m][0], a1 = acc[ai][0][m][1], b0 = acc[ai][1][m][0], b1 = acc[ai][1][m][1];
;                 bf16_t* p = OUT + (size_t)row * 1024 + pn * 256 + cw;
;                 st8(p, a0, a1); st8(p + HALF, b0, b1);
;                 const float pa = red_fq(ssq4(a0) + ssq4(a1)), pb = red_fq(ssq4(b0) + ssq4(b1));
;                 if (fq == 0) { SSQ[(size_t)row * 32 + pn * 8 + wc] = pa; SSQ[(size_t)row * 32 + pn * 8 + 4 + wc] = pb; }
.LBB0_685:
	s_or_b64 exec, exec, s[0:1]
	v_add_u32_e32 v48, 0x90, v146
	v_ashrrev_i32_e32 v49, 31, v48
	v_lshlrev_b64 v[50:51], 11, v[48:49]
	v_lshl_add_u64 v[50:51], s[10:11], 0, v[50:51]
	v_lshl_add_u64 v[50:51], s[34:35], 1, v[50:51]
	v_lshl_add_u64 v[54:55], v[144:145], 1, v[50:51]
	v_cvt_pk_bf16_f32 v50, v44, v45
	v_cvt_pk_bf16_f32 v51, v46, v47
	v_cvt_pk_bf16_f32 v52, v40, v41
	v_mul_f32_e32 v45, v45, v45
	v_mul_f32_e32 v41, v41, v41
	v_fmac_f32_e32 v45, v44, v44
	v_mul_f32_e32 v44, v47, v47
	v_fmac_f32_e32 v41, v40, v40
	v_mul_f32_e32 v40, v43, v43
	s_waitcnt lgkmcnt(0)
	v_cvt_pk_bf16_f32 v53, v42, v43
	v_fmac_f32_e32 v44, v46, v46
	v_fmac_f32_e32 v40, v42, v42
	v_mul_f32_e32 v42, v37, v37
	v_mul_f32_e32 v43, v39, v39
	v_add_f32_e32 v44, v45, v44
	v_add_f32_e32 v40, v41, v40
	v_fmac_f32_e32 v42, v36, v36
	v_fmac_f32_e32 v43, v38, v38
	v_add_f32_e32 v40, v40, v44
	v_add_f32_e32 v42, v42, v43
	v_mul_f32_e32 v43, v33, v33
	v_mul_f32_e32 v44, v35, v35
	v_fmac_f32_e32 v43, v32, v32
	v_fmac_f32_e32 v44, v34, v34
	v_add_f32_e32 v43, v43, v44
	v_add_f32_e32 v43, v43, v42
	v_mov_b32_e32 v41, v40
	v_mov_b32_e32 v44, v43
	s_nop 1
	v_permlane16_swap_b32_e32 v41, v40
	v_permlane16_swap_b32_e32 v44, v43
	global_store_dwordx4 v[54:55], v[50:53], off
	v_cvt_pk_bf16_f32 v42, v36, v37
	s_waitcnt lgkmcnt(0)
	v_add_f32_e32 v36, v40, v41
	v_add_f32_e32 v40, v43, v44
	v_mov_b32_e32 v37, v36
	v_mov_b32_e32 v41, v40
	s_nop 1
	v_permlane32_swap_b32_e32 v37, v36
	v_permlane32_swap_b32_e32 v41, v40
	v_cvt_pk_bf16_f32 v43, v38, v39
	v_cvt_pk_bf16_f32 v44, v32, v33
	v_cvt_pk_bf16_f32 v45, v34, v35
	global_store_dwordx4 v[54:55], v[42:45], off offset:256
	s_and_saveexec_b64 s[0:1], vcc
	s_cbranch_execz .LBB0_687
	v_lshlrev_b64 v[32:33], 7, v[48:49]
	v_lshl_add_u64 v[32:33], s[18:19], 0, v[32:33]
	v_lshl_add_u64 v[32:33], s[30:31], 2, v[32:33]
	s_waitcnt lgkmcnt(0)
	v_add_f32_e32 v35, v36, v37
	v_lshl_add_u64 v[32:33], s[6:7], 2, v[32:33]
	v_add_f32_e32 v34, v40, v41
	global_store_dword v[32:33], v35, off
	global_store_dword v[32:33], v34, off offset:16
.LBB0_687:
	s_or_b64 exec, exec, s[0:1]
	v_add_u32_e32 v32, 0xa0, v146
	v_ashrrev_i32_e32 v33, 31, v32
	v_lshlrev_b64 v[34:35], 11, v[32:33]
	v_lshl_add_u64 v[34:35], s[10:11], 0, v[34:35]
	v_lshl_add_u64 v[34:35], s[34:35], 1, v[34:35]
	v_lshl_add_u64 v[38:39], v[144:145], 1, v[34:35]
	v_cvt_pk_bf16_f32 v34, v28, v29
	v_cvt_pk_bf16_f32 v35, v30, v31
	v_cvt_pk_bf16_f32 v36, v24, v25
	v_mul_f32_e32 v29, v29, v29
	v_mul_f32_e32 v25, v25, v25
	v_fmac_f32_e32 v29, v28, v28
	v_mul_f32_e32 v28, v31, v31
	v_fmac_f32_e32 v25, v24, v24
	v_mul_f32_e32 v24, v27, v27
	s_waitcnt lgkmcnt(0)
	v_cvt_pk_bf16_f32 v37, v26, v27
	v_fmac_f32_e32 v28, v30, v30
	v_fmac_f32_e32 v24, v26, v26
	v_mul_f32_e32 v26, v21, v21
	v_mul_f32_e32 v27, v23, v23
	v_add_f32_e32 v28, v29, v28
	v_add_f32_e32 v24, v25, v24
	v_fmac_f32_e32 v26, v20, v20
	v_fmac_f32_e32 v27, v22, v22
	v_add_f32_e32 v24, v24, v28
	v_add_f32_e32 v26, v26, v27
	v_mul_f32_e32 v27, v17, v17
	v_mul_f32_e32 v28, v19, v19
	v_fmac_f32_e32 v27, v16, v16
	v_fmac_f32_e32 v28, v18, v18
	v_add_f32_e32 v27, v27, v28
	v_add_f32_e32 v27, v27, v26
	v_mov_b32_e32 v25, v24
	v_mov_b32_e32 v28, v27
	s_nop 1
	v_permlane16_swap_b32_e32 v25, v24
	v_permlane16_swap_b32_e32 v28, v27
	global_store_dwordx4 v[38:39], v[34:37], off
	v_cvt_pk_bf16_f32 v26, v20, v21
	s_waitcnt lgkmcnt(0)
	v_add_f32_e32 v20, v24, v25
	v_add_f32_e32 v24, v27, v28
	v_mov_b32_e32 v21, v20
	v_mov_b32_e32 v25, v24
	s_nop 1
	v_permlane32_swap_b32_e32 v21, v20
	v_permlane32_swap_b32_e32 v25, v24
	v_cvt_pk_bf16_f32 v27, v22, v23
	v_cvt_pk_bf16_f32 v28, v16, v17
	v_cvt_pk_bf16_f32 v29, v18, v19
	global_store_dwordx4 v[38:39], v[26:29], off offset:256
	s_and_saveexec_b64 s[0:1], vcc
	s_cbranch_execz .LBB0_689
	v_lshlrev_b64 v[16:17], 7, v[32:33]
	v_lshl_add_u64 v[16:17], s[18:19], 0, v[16:17]
	v_lshl_add_u64 v[16:17], s[30:31], 2, v[16:17]
	s_waitcnt lgkmcnt(0)
	v_add_f32_e32 v19, v20, v21
	v_lshl_add_u64 v[16:17], s[6:7], 2, v[16:17]
	v_add_f32_e32 v18, v24, v25
	global_store_dword v[16:17], v19, off
	global_store_dword v[16:17], v18, off offset:16
.LBB0_689:
	s_or_b64 exec, exec, s[0:1]
	v_add_u32_e32 v16, 0xb0, v146
	v_ashrrev_i32_e32 v17, 31, v16
	v_lshlrev_b64 v[18:19], 11, v[16:17]
	v_lshl_add_u64 v[18:19], s[10:11], 0, v[18:19]
	v_lshl_add_u64 v[18:19], s[34:35], 1, v[18:19]
	v_lshl_add_u64 v[22:23], v[144:145], 1, v[18:19]
	v_cvt_pk_bf16_f32 v18, v12, v13
	v_cvt_pk_bf16_f32 v19, v14, v15
	v_cvt_pk_bf16_f32 v20, v8, v9
	v_mul_f32_e32 v13, v13, v13
	v_mul_f32_e32 v9, v9, v9
	v_fmac_f32_e32 v13, v12, v12
	v_mul_f32_e32 v12, v15, v15
	v_fmac_f32_e32 v9, v8, v8
	v_mul_f32_e32 v8, v11, v11
	s_waitcnt lgkmcnt(0)
	v_cvt_pk_bf16_f32 v21, v10, v11
	v_fmac_f32_e32 v12, v14, v14
	v_fmac_f32_e32 v8, v10, v10
	v_mul_f32_e32 v10, v5, v5
	v_mul_f32_e32 v11, v7, v7
	v_add_f32_e32 v12, v13, v12
	v_add_f32_e32 v8, v9, v8
	v_fmac_f32_e32 v10, v4, v4
	v_fmac_f32_e32 v11, v6, v6
	v_add_f32_e32 v8, v8, v12
	v_add_f32_e32 v10, v10, v11
	v_mul_f32_e32 v11, v1, v1
	v_mul_f32_e32 v12, v3, v3
	v_fmac_f32_e32 v11, v0, v0
	v_fmac_f32_e32 v12, v2, v2
	v_add_f32_e32 v11, v11, v12
	v_add_f32_e32 v11, v11, v10
	v_mov_b32_e32 v9, v8
	v_mov_b32_e32 v12, v11
	s_nop 1
	v_permlane16_swap_b32_e32 v9, v8
	v_permlane16_swap_b32_e32 v12, v11
	global_store_dwordx4 v[22:23], v[18:21], off
	v_cvt_pk_bf16_f32 v10, v4, v5
	s_waitcnt lgkmcnt(0)
	v_add_f32_e32 v4, v8, v9
	v_add_f32_e32 v8, v11, v12
	v_mov_b32_e32 v5, v4
	v_mov_b32_e32 v9, v8
	s_nop 1
	v_permlane32_swap_b32_e32 v5, v4
	v_permlane32_swap_b32_e32 v9, v8
	v_cvt_pk_bf16_f32 v11, v6, v7
	v_cvt_pk_bf16_f32 v12, v0, v1
	v_cvt_pk_bf16_f32 v13, v2, v3
	global_store_dwordx4 v[22:23], v[10:13], off offset:256
	s_and_saveexec_b64 s[0:1], vcc
	s_cbranch_execz .LBB0_691
	v_lshlrev_b64 v[0:1], 7, v[16:17]
	v_lshl_add_u64 v[0:1], s[18:19], 0, v[0:1]
	v_lshl_add_u64 v[0:1], s[30:31], 2, v[0:1]
	s_waitcnt lgkmcnt(0)
	v_add_f32_e32 v3, v4, v5
	v_lshl_add_u64 v[0:1], s[6:7], 2, v[0:1]
	v_add_f32_e32 v2, v8, v9
	global_store_dword v[0:1], v3, off
	global_store_dword v[0:1], v2, off offset:16

; __device__ __forceinline__ unsigned cvt_pk_bf16(float lo, float hi) { unsigned r; asm volatile("v_cvt_pk_bf16_f32 %0, %1, %2" : "=v"(r) : "v"(lo), "v"(hi)); return r; }
; __device__ __forceinline__ void st8(bf16_t* p, f32x4 a, f32x4 b) { u32x4 w; w.x = cvt_pk_bf16(a[0], a[1]); w.y = cvt_pk_bf16(a[2], a[3]); w.z = cvt_pk_bf16(b[0], b[1]); w.w = cvt_pk_bf16(b[2], b[3]); *(u32x4*)p = w; }
; __device__ __forceinline__ float ssq4(f32x4 a) { return (a[0] * a[0] + a[1] * a[1]) + (a[2] * a[2] + a[3] * a[3]); }
; __device__ __forceinline__ float red_fq(float p) { p += __shfl_xor(p, 16); p += __shfl_xor(p, 32); return p; }
;     __device__ __forceinline__ void operator()(const f32x4 (&acc)[2][2][4][2], const Unit& u, int wr, int wc, int fr, int fq) const {
;     ...
;                 const int row = row0 + ai * HALF + m * 16;
;                 const f32x4 a0 = acc[ai][0][m][0], a1 = acc[ai][0][m][1], b0 = acc[ai][1][m][0], b1 = acc[ai][1][m][1];
;                 bf16_t* p = OUT + (size_t)row * 1024 + pn * 256 + cw;
;                 st8(p, a0, a1); st8(p + HALF, b0, b1);
;                 const float pa = red_fq(ssq4(a0) + ssq4(a1)), pb = red_fq(ssq4(b0) + ssq4(b1));
;                 if (fq == 0) { SSQ[(size_t)row * 32 + pn * 8 + wc] = pa; SSQ[(size_t)row * 32 + pn * 8 + 4 + wc] = pb; }
.LBB0_887:
	v_mov_b32_e32 v145, v148
	v_mov_b32_e32 v147, v149
	s_mov_b32 s0, s41
	s_mov_b32 s28, s50
	s_lshl_b32 s1, s34, 8
	s_lshl_b32 s0, s0, 6
	s_add_i32 s0, s0, s1
	v_add_u32_e32 v146, s0, v145
	v_lshlrev_b32_e32 v144, 3, v147
	v_cmp_eq_u32_e32 vcc, 0, v147
	v_ashrrev_i32_e32 v147, 31, v146
	s_lshl_b32 s34, s60, 8
	v_lshlrev_b64 v[156:157], 11, v[146:147]
	v_lshl_add_u32 v144, s28, 5, v144
	s_ashr_i32 s35, s34, 31
	v_lshl_add_u64 v[156:157], s[14:15], 0, v[156:157]
	v_ashrrev_i32_e32 v145, 31, v144
	v_lshl_add_u64 v[156:157], s[34:35], 1, v[156:157]
	v_lshl_add_u64 v[160:161], v[144:145], 1, v[156:157]
	v_cvt_pk_bf16_f32 v156, v124, v125
	v_mul_f32_e32 v125, v125, v125
	v_fmac_f32_e32 v125, v124, v124
	v_mul_f32_e32 v124, v127, v127
	v_fmac_f32_e32 v124, v126, v126
	v_cvt_pk_bf16_f32 v157, v126, v127
	v_add_f32_e32 v124, v125, v124
	v_mul_f32_e32 v125, v121, v121
	v_mul_f32_e32 v126, v123, v123
	v_cvt_pk_bf16_f32 v158, v120, v121
	v_cvt_pk_bf16_f32 v159, v122, v123
	global_store_dwordx4 v[160:161], v[156:159], off
	v_fmac_f32_e32 v125, v120, v120
	v_fmac_f32_e32 v126, v122, v122
	v_cvt_pk_bf16_f32 v156, v116, v117
	v_mul_f32_e32 v117, v117, v117
	v_fmac_f32_e32 v117, v116, v116
	v_mul_f32_e32 v116, v119, v119
	v_add_f32_e32 v125, v125, v126
	v_and_b32_e32 v126, 64, v154
	v_fmac_f32_e32 v116, v118, v118
	v_add_f32_e32 v125, v125, v124
	v_xor_b32_e32 v124, 16, v154
	v_add_u32_e32 v126, 64, v126
	v_add_f32_e32 v116, v117, v116
	v_mul_f32_e32 v117, v113, v113
	v_mul_f32_e32 v122, v115, v115
	v_cmp_lt_i32_e64 s[0:1], v124, v126
	v_fmac_f32_e32 v117, v112, v112
	v_fmac_f32_e32 v122, v114, v114
	v_cndmask_b32_e64 v124, v154, v124, s[0:1]
	v_add_f32_e32 v117, v117, v122
	v_lshlrev_b32_e32 v124, 2, v124
	v_add_f32_e32 v122, v117, v116
	v_mov_b32_e32 v127, v125
	v_mov_b32_e32 v123, v122
	s_nop 1
	v_permlane16_swap_b32_e32 v127, v125
	v_permlane16_swap_b32_e32 v123, v122
	v_xor_b32_e32 v121, 32, v154
	v_cmp_lt_i32_e64 s[0:1], v121, v126
	s_lshl_b32 s30, s60, 3
	s_waitcnt lgkmcnt(0)
	v_add_f32_e32 v120, v125, v127
	v_cndmask_b32_e64 v116, v154, v121, s[0:1]
	v_lshlrev_b32_e32 v116, 2, v116
	v_add_f32_e32 v121, v122, v123
	v_mov_b32_e32 v117, v120
	v_mov_b32_e32 v122, v121
	s_nop 1
	v_permlane32_swap_b32_e32 v117, v120
	v_permlane32_swap_b32_e32 v122, v121
	s_ashr_i32 s31, s30, 31
	s_ashr_i32 s29, s28, 31
	v_cvt_pk_bf16_f32 v157, v118, v119
	v_cvt_pk_bf16_f32 v158, v112, v113
	v_cvt_pk_bf16_f32 v159, v114, v115
	global_store_dwordx4 v[160:161], v[156:159], off offset:256
	s_and_saveexec_b64 s[0:1], vcc
	s_cbranch_execz .LBB0_889
	v_lshlrev_b64 v[112:113], 7, v[146:147]
	v_lshl_add_u64 v[112:113], s[16:17], 0, v[112:113]
	v_lshl_add_u64 v[112:113], s[30:31], 2, v[112:113]
	s_waitcnt lgkmcnt(0)
	v_add_f32_e32 v115, v120, v117
	v_lshl_add_u64 v[112:113], s[28:29], 2, v[112:113]
	v_add_f32_e32 v114, v121, v122
	global_store_dword v[112:113], v115, off
	global_store_dword v[112:113], v114, off offset:16
.LBB0_889:
	s_or_b64 exec, exec, s[0:1]
	v_cvt_pk_bf16_f32 v118, v108, v109
	v_cvt_pk_bf16_f32 v119, v110, v111
	v_cvt_pk_bf16_f32 v120, v104, v105
	v_mul_f32_e32 v109, v109, v109
	v_mul_f32_e32 v105, v105, v105
	v_fmac_f32_e32 v109, v108, v108
	v_mul_f32_e32 v108, v111, v111
	v_fmac_f32_e32 v105, v104, v104
	v_mul_f32_e32 v104, v107, v107
	v_cvt_pk_bf16_f32 v121, v106, v107
	v_fmac_f32_e32 v108, v110, v110
	v_fmac_f32_e32 v104, v106, v106
	v_mul_f32_e32 v106, v101, v101
	v_mul_f32_e32 v107, v103, v103
	v_add_f32_e32 v108, v109, v108
	v_add_f32_e32 v104, v105, v104
	v_fmac_f32_e32 v106, v100, v100
	v_fmac_f32_e32 v107, v102, v102
	v_add_f32_e32 v104, v104, v108
	v_add_f32_e32 v106, v106, v107
	v_mul_f32_e32 v107, v97, v97
	v_mul_f32_e32 v108, v99, v99
	v_fmac_f32_e32 v107, v96, v96
	v_fmac_f32_e32 v108, v98, v98
	v_add_f32_e32 v107, v107, v108
	v_add_u32_e32 v112, 16, v146
	v_add_f32_e32 v107, v107, v106
	v_ashrrev_i32_e32 v113, 31, v112
	v_mov_b32_e32 v105, v104
	v_mov_b32_e32 v108, v107
	s_nop 1
	v_permlane16_swap_b32_e32 v105, v104
	v_permlane16_swap_b32_e32 v108, v107
	v_lshlrev_b64 v[114:115], 11, v[112:113]
	v_lshl_add_u64 v[114:115], s[14:15], 0, v[114:115]
	v_lshl_add_u64 v[114:115], s[34:35], 1, v[114:115]
	v_lshl_add_u64 v[114:115], v[144:145], 1, v[114:115]
	global_store_dwordx4 v[114:115], v[118:121], off
	v_cvt_pk_bf16_f32 v106, v100, v101
	s_waitcnt lgkmcnt(0)
	v_add_f32_e32 v100, v104, v105
	v_add_f32_e32 v104, v107, v108
	v_mov_b32_e32 v101, v100
	v_mov_b32_e32 v105, v104
	s_nop 1
	v_permlane32_swap_b32_e32 v101, v100
	v_permlane32_swap_b32_e32 v105, v104
	v_cvt_pk_bf16_f32 v107, v102, v103
	v_cvt_pk_bf16_f32 v108, v96, v97
	v_cvt_pk_bf16_f32 v109, v98, v99
	global_store_dwordx4 v[114:115], v[106:109], off offset:256
	s_and_saveexec_b64 s[0:1], vcc
	s_cbranch_execz .LBB0_891
	v_lshlrev_b64 v[96:97], 7, v[112:113]
	v_lshl_add_u64 v[96:97], s[16:17], 0, v[96:97]
	v_lshl_add_u64 v[96:97], s[30:31], 2, v[96:97]
	s_waitcnt lgkmcnt(0)
	v_add_f32_e32 v99, v100, v101
	v_lshl_add_u64 v[96:97], s[28:29], 2, v[96:97]
	v_add_f32_e32 v98, v104, v105
	global_store_dword v[96:97], v99, off
	global_store_dword v[96:97], v98, off offset:16
; __device__ __forceinline__ unsigned cvt_pk_bf16(float lo, float hi) { unsigned r; asm volatile("v_cvt_pk_bf16_f32 %0, %1, %2" : "=v"(r) : "v"(lo), "v"(hi)); return r; }
; __device__ __forceinline__ void st8(bf16_t* p, f32x4 a, f32x4 b) { u32x4 w; w.x = cvt_pk_bf16(a[0], a[1]); w.y = cvt_pk_bf16(a[2], a[3]); w.z = cvt_pk_bf16(b[0], b[1]); w.w = cvt_pk_bf16(b[2], b[3]); *(u32x4*)p = w; }
; __device__ __forceinline__ float ssq4(f32x4 a) { return (a[0] * a[0] + a[1] * a[1]) + (a[2] * a[2] + a[3] * a[3]); }
; __device__ __forceinline__ float red_fq(float p) { p += __shfl_xor(p, 16); p += __shfl_xor(p, 32); return p; }
;     __device__ __forceinline__ void operator()(const f32x4 (&acc)[2][2][4][2], const Unit& u, int wr, int wc, int fr, int fq) const {
;     ...
;                 const int row = row0 + ai * HALF + m * 16;
;                 const f32x4 a0 = acc[ai][0][m][0], a1 = acc[ai][0][m][1], b0 = acc[ai][1][m][0], b1 = acc[ai][1][m][1];
;                 bf16_t* p = OUT + (size_t)row * 1024 + pn * 256 + cw;
;                 st8(p, a0, a1); st8(p + HALF, b0, b1);
;                 const float pa = red_fq(ssq4(a0) + ssq4(a1)), pb = red_fq(ssq4(b0) + ssq4(b1));
;                 if (fq == 0) { SSQ[(size_t)row * 32 + pn * 8 + wc] = pa; SSQ[(size_t)row * 32 + pn * 8 + 4 + wc] = pb; }
.LBB0_891:
	s_or_b64 exec, exec, s[0:1]
	v_add_u32_e32 v96, 32, v146
	v_ashrrev_i32_e32 v97, 31, v96
	v_lshlrev_b64 v[98:99], 11, v[96:97]
	v_lshl_add_u64 v[98:99], s[14:15], 0, v[98:99]
	v_lshl_add_u64 v[98:99], s[34:35], 1, v[98:99]
	v_lshl_add_u64 v[102:103], v[144:145], 1, v[98:99]
	v_cvt_pk_bf16_f32 v98, v92, v93
	v_cvt_pk_bf16_f32 v99, v94, v95
	v_cvt_pk_bf16_f32 v100, v88, v89
	v_mul_f32_e32 v93, v93, v93
	v_mul_f32_e32 v89, v89, v89
	v_fmac_f32_e32 v93, v92, v92
	v_mul_f32_e32 v92, v95, v95
	v_fmac_f32_e32 v89, v88, v88
	v_mul_f32_e32 v88, v91, v91
	s_waitcnt lgkmcnt(0)
	v_cvt_pk_bf16_f32 v101, v90, v91
	v_fmac_f32_e32 v92, v94, v94
	v_fmac_f32_e32 v88, v90, v90
	v_mul_f32_e32 v90, v85, v85
	v_mul_f32_e32 v91, v87, v87
	v_add_f32_e32 v92, v93, v92
	v_add_f32_e32 v88, v89, v88
	v_fmac_f32_e32 v90, v84, v84
	v_fmac_f32_e32 v91, v86, v86
	v_add_f32_e32 v88, v88, v92
	v_add_f32_e32 v90, v90, v91
	v_mul_f32_e32 v91, v81, v81
	v_mul_f32_e32 v92, v83, v83
	v_fmac_f32_e32 v91, v80, v80
	v_fmac_f32_e32 v92, v82, v82
	v_add_f32_e32 v91, v91, v92
	v_add_f32_e32 v91, v91, v90
	v_mov_b32_e32 v89, v88
	v_mov_b32_e32 v92, v91
	s_nop 1
	v_permlane16_swap_b32_e32 v89, v88
	v_permlane16_swap_b32_e32 v92, v91
	global_store_dwordx4 v[102:103], v[98:101], off
	v_cvt_pk_bf16_f32 v90, v84, v85
	s_waitcnt lgkmcnt(0)
	v_add_f32_e32 v84, v88, v89
	v_add_f32_e32 v88, v91, v92
	v_mov_b32_e32 v85, v84
	v_mov_b32_e32 v89, v88
	s_nop 1
	v_permlane32_swap_b32_e32 v85, v84
	v_permlane32_swap_b32_e32 v89, v88
	v_cvt_pk_bf16_f32 v91, v86, v87
	v_cvt_pk_bf16_f32 v92, v80, v81
	v_cvt_pk_bf16_f32 v93, v82, v83
	global_store_dwordx4 v[102:103], v[90:93], off offset:256
	s_and_saveexec_b64 s[0:1], vcc
	s_cbranch_execz .LBB0_893
	v_lshlrev_b64 v[80:81], 7, v[96:97]
	v_lshl_add_u64 v[80:81], s[16:17], 0, v[80:81]
	v_lshl_add_u64 v[80:81], s[30:31], 2, v[80:81]
	s_waitcnt lgkmcnt(0)
	v_add_f32_e32 v83, v84, v85
	v_lshl_add_u64 v[80:81], s[28:29], 2, v[80:81]
	v_add_f32_e32 v82, v88, v89
	global_store_dword v[80:81], v83, off
	global_store_dword v[80:81], v82, off offset:16
.LBB0_893:
	s_or_b64 exec, exec, s[0:1]
	v_add_u32_e32 v80, 48, v146
	v_ashrrev_i32_e32 v81, 31, v80
	v_lshlrev_b64 v[82:83], 11, v[80:81]
	v_lshl_add_u64 v[82:83], s[14:15], 0, v[82:83]
	v_lshl_add_u64 v[82:83], s[34:35], 1, v[82:83]
	v_lshl_add_u64 v[86:87], v[144:145], 1, v[82:83]
	v_cvt_pk_bf16_f32 v82, v76, v77
	v_cvt_pk_bf16_f32 v83, v78, v79
	v_cvt_pk_bf16_f32 v84, v72, v73
	v_mul_f32_e32 v77, v77, v77
	v_mul_f32_e32 v73, v73, v73
	v_fmac_f32_e32 v77, v76, v76
	v_mul_f32_e32 v76, v79, v79
	v_fmac_f32_e32 v73, v72, v72
	v_mul_f32_e32 v72, v75, v75
	s_waitcnt lgkmcnt(0)
	v_cvt_pk_bf16_f32 v85, v74, v75
	v_fmac_f32_e32 v76, v78, v78
	v_fmac_f32_e32 v72, v74, v74
	v_mul_f32_e32 v74, v69, v69
	v_mul_f32_e32 v75, v71, v71
	v_add_f32_e32 v76, v77, v76
	v_add_f32_e32 v72, v73, v72
	v_fmac_f32_e32 v74, v68, v68
	v_fmac_f32_e32 v75, v70, v70
	v_add_f32_e32 v72, v72, v76
	v_add_f32_e32 v74, v74, v75
	v_mul_f32_e32 v75, v65, v65
	v_mul_f32_e32 v76, v67, v67
	v_fmac_f32_e32 v75, v64, v64
	v_fmac_f32_e32 v76, v66, v66
	v_add_f32_e32 v75, v75, v76
	v_add_f32_e32 v75, v75, v74
	v_mov_b32_e32 v73, v72
	v_mov_b32_e32 v76, v75
	s_nop 1
	v_permlane16_swap_b32_e32 v73, v72
	v_permlane16_swap_b32_e32 v76, v75
	global_store_dwordx4 v[86:87], v[82:85], off
	v_cvt_pk_bf16_f32 v74, v68, v69
	s_waitcnt lgkmcnt(0)
	v_add_f32_e32 v68, v72, v73
	v_add_f32_e32 v72, v75, v76
	v_mov_b32_e32 v69, v68
	v_mov_b32_e32 v73, v72
	s_nop 1
	v_permlane32_swap_b32_e32 v69, v68
	v_permlane32_swap_b32_e32 v73, v72
	v_cvt_pk_bf16_f32 v75, v70, v71
	v_cvt_pk_bf16_f32 v76, v64, v65
	v_cvt_pk_bf16_f32 v77, v66, v67
	global_store_dwordx4 v[86:87], v[74:77], off offset:256
	s_and_saveexec_b64 s[0:1], vcc
	s_cbranch_execz .LBB0_895
	v_lshlrev_b64 v[64:65], 7, v[80:81]
	v_lshl_add_u64 v[64:65], s[16:17], 0, v[64:65]
	v_lshl_add_u64 v[64:65], s[30:31], 2, v[64:65]
	s_waitcnt lgkmcnt(0)
	v_add_f32_e32 v67, v68, v69
	v_lshl_add_u64 v[64:65], s[28:29], 2, v[64:65]
	v_add_f32_e32 v66, v72, v73
	global_store_dword v[64:65], v67, off
	global_store_dword v[64:65], v66, off offset:16
.LBB0_895:
	s_or_b64 exec, exec, s[0:1]
	v_add_u32_e32 v64, 0x80, v146
	v_ashrrev_i32_e32 v65, 31, v64
	v_lshlrev_b64 v[66:67], 11, v[64:65]
	v_lshl_add_u64 v[66:67], s[14:15], 0, v[66:67]
	v_lshl_add_u64 v[66:67], s[34:35], 1, v[66:67]
	v_lshl_add_u64 v[70:71], v[144:145], 1, v[66:67]
	v_cvt_pk_bf16_f32 v66, v60, v61
	v_cvt_pk_bf16_f32 v67, v62, v63
	v_cvt_pk_bf16_f32 v68, v56, v57
	v_mul_f32_e32 v61, v61, v61
	v_mul_f32_e32 v57, v57, v57
	v_fmac_f32_e32 v61, v60, v60
	v_mul_f32_e32 v60, v63, v63
	v_fmac_f32_e32 v57, v56, v56
	v_mul_f32_e32 v56, v59, v59
	s_waitcnt lgkmcnt(0)
	v_cvt_pk_bf16_f32 v69, v58, v59
	v_fmac_f32_e32 v60, v62, v62
	v_fmac_f32_e32 v56, v58, v58
	v_mul_f32_e32 v58, v53, v53
	v_mul_f32_e32 v59, v55, v55
	v_add_f32_e32 v60, v61, v60
	v_add_f32_e32 v56, v57, v56
	v_fmac_f32_e32 v58, v52, v52
	v_fmac_f32_e32 v59, v54, v54
	v_add_f32_e32 v56, v56, v60
	v_add_f32_e32 v58, v58, v59
	v_mul_f32_e32 v59, v49, v49
	v_mul_f32_e32 v60, v51, v51
	v_fmac_f32_e32 v59, v48, v48
	v_fmac_f32_e32 v60, v50, v50
	v_add_f32_e32 v59, v59, v60
	v_add_f32_e32 v59, v59, v58
	v_mov_b32_e32 v57, v56
	v_mov_b32_e32 v60, v59
	s_nop 1
	v_permlane16_swap_b32_e32 v57, v56
	v_permlane16_swap_b32_e32 v60, v59
	global_store_dwordx4 v[70:71], v[66:69], off
	v_cvt_pk_bf16_f32 v58, v52, v53
	s_waitcnt lgkmcnt(0)
	v_add_f32_e32 v52, v56, v57
	v_add_f32_e32 v56, v59, v60
	v_mov_b32_e32 v53, v52
	v_mov_b32_e32 v57, v56
	s_nop 1
	v_permlane32_swap_b32_e32 v53, v52
	v_permlane32_swap_b32_e32 v57, v56
	v_cvt_pk_bf16_f32 v59, v54, v55
	v_cvt_pk_bf16_f32 v60, v48, v49
	v_cvt_pk_bf16_f32 v61, v50, v51
	global_store_dwordx4 v[70:71], v[58:61], off offset:256
	s_and_saveexec_b64 s[0:1], vcc
	s_cbranch_execz .LBB0_897
	v_lshlrev_b64 v[48:49], 7, v[64:65]
	v_lshl_add_u64 v[48:49], s[16:17], 0, v[48:49]
	v_lshl_add_u64 v[48:49], s[30:31], 2, v[48:49]
	s_waitcnt lgkmcnt(0)
	v_add_f32_e32 v51, v52, v53
	v_lshl_add_u64 v[48:49], s[28:29], 2, v[48:49]
	v_add_f32_e32 v50, v56, v57
	global_store_dword v[48:49], v51, off
	global_store_dword v[48:49], v50, off offset:16
; __device__ __forceinline__ unsigned cvt_pk_bf16(float lo, float hi) { unsigned r; asm volatile("v_cvt_pk_bf16_f32 %0, %1, %2" : "=v"(r) : "v"(lo), "v"(hi)); return r; }
; __device__ __forceinline__ void st8(bf16_t* p, f32x4 a, f32x4 b) { u32x4 w; w.x = cvt_pk_bf16(a[0], a[1]); w.y = cvt_pk_bf16(a[2], a[3]); w.z = cvt_pk_bf16(b[0], b[1]); w.w = cvt_pk_bf16(b[2], b[3]); *(u32x4*)p = w; }
; __device__ __forceinline__ float ssq4(f32x4 a) { return (a[0] * a[0] + a[1] * a[1]) + (a[2] * a[2] + a[3] * a[3]); }
; __device__ __forceinline__ float red_fq(float p) { p += __shfl_xor(p, 16); p += __shfl_xor(p, 32); return p; }
;     __device__ __forceinline__ void operator()(const f32x4 (&acc)[2][2][4][2], const Unit& u, int wr, int wc, int fr, int fq) const {
;     ...
;                 const int row = row0 + ai * HALF + m * 16;
;                 const f32x4 a0 = acc[ai][0][m][0], a1 = acc[ai][0][m][1], b0 = acc[ai][1][m][0], b1 = acc[ai][1][m][1];
;                 bf16_t* p = OUT + (size_t)row * 1024 + pn * 256 + cw;
;                 st8(p, a0, a1); st8(p + HALF, b0, b1);
;                 const float pa = red_fq(ssq4(a0) + ssq4(a1)), pb = red_fq(ssq4(b0) + ssq4(b1));
;                 if (fq == 0) { SSQ[(size_t)row * 32 + pn * 8 + wc] = pa; SSQ[(size_t)row * 32 + pn * 8 + 4 + wc] = pb; }
.LBB0_897:
	s_or_b64 exec, exec, s[0:1]
	v_add_u32_e32 v48, 0x90, v146
	v_ashrrev_i32_e32 v49, 31, v48
	v_lshlrev_b64 v[50:51], 11, v[48:49]
	v_lshl_add_u64 v[50:51], s[14:15], 0, v[50:51]
	v_lshl_add_u64 v[50:51], s[34:35], 1, v[50:51]
	v_lshl_add_u64 v[54:55], v[144:145], 1, v[50:51]
	v_cvt_pk_bf16_f32 v50, v44, v45
	v_cvt_pk_bf16_f32 v51, v46, v47
	v_cvt_pk_bf16_f32 v52, v40, v41
	v_mul_f32_e32 v45, v45, v45
	v_mul_f32_e32 v41, v41, v41
	v_fmac_f32_e32 v45, v44, v44
	v_mul_f32_e32 v44, v47, v47
	v_fmac_f32_e32 v41, v40, v40
	v_mul_f32_e32 v40, v43, v43
	s_waitcnt lgkmcnt(0)
	v_cvt_pk_bf16_f32 v53, v42, v43
	v_fmac_f32_e32 v44, v46, v46
	v_fmac_f32_e32 v40, v42, v42
	v_mul_f32_e32 v42, v37, v37
	v_mul_f32_e32 v43, v39, v39
	v_add_f32_e32 v44, v45, v44
	v_add_f32_e32 v40, v41, v40
	v_fmac_f32_e32 v42, v36, v36
	v_fmac_f32_e32 v43, v38, v38
	v_add_f32_e32 v40, v40, v44
	v_add_f32_e32 v42, v42, v43
	v_mul_f32_e32 v43, v33, v33
	v_mul_f32_e32 v44, v35, v35
	v_fmac_f32_e32 v43, v32, v32
	v_fmac_f32_e32 v44, v34, v34
	v_add_f32_e32 v43, v43, v44
	v_add_f32_e32 v43, v43, v42
	v_mov_b32_e32 v41, v40
	v_mov_b32_e32 v44, v43
	s_nop 1
	v_permlane16_swap_b32_e32 v41, v40
	v_permlane16_swap_b32_e32 v44, v43
	global_store_dwordx4 v[54:55], v[50:53], off
	v_cvt_pk_bf16_f32 v42, v36, v37
	s_waitcnt lgkmcnt(0)
	v_add_f32_e32 v36, v40, v41
	v_add_f32_e32 v40, v43, v44
	v_mov_b32_e32 v37, v36
	v_mov_b32_e32 v41, v40
	s_nop 1
	v_permlane32_swap_b32_e32 v37, v36
	v_permlane32_swap_b32_e32 v41, v40
	v_cvt_pk_bf16_f32 v43, v38, v39
	v_cvt_pk_bf16_f32 v44, v32, v33
	v_cvt_pk_bf16_f32 v45, v34, v35
	global_store_dwordx4 v[54:55], v[42:45], off offset:256
	s_and_saveexec_b64 s[0:1], vcc
	s_cbranch_execz .LBB0_899
	v_lshlrev_b64 v[32:33], 7, v[48:49]
	v_lshl_add_u64 v[32:33], s[16:17], 0, v[32:33]
	v_lshl_add_u64 v[32:33], s[30:31], 2, v[32:33]
	s_waitcnt lgkmcnt(0)
	v_add_f32_e32 v35, v36, v37
	v_lshl_add_u64 v[32:33], s[28:29], 2, v[32:33]
	v_add_f32_e32 v34, v40, v41
	global_store_dword v[32:33], v35, off
	global_store_dword v[32:33], v34, off offset:16
.LBB0_899:
	s_or_b64 exec, exec, s[0:1]
	v_add_u32_e32 v32, 0xa0, v146
	v_ashrrev_i32_e32 v33, 31, v32
	v_lshlrev_b64 v[34:35], 11, v[32:33]
	v_lshl_add_u64 v[34:35], s[14:15], 0, v[34:35]
	v_lshl_add_u64 v[34:35], s[34:35], 1, v[34:35]
	v_lshl_add_u64 v[38:39], v[144:145], 1, v[34:35]
	v_cvt_pk_bf16_f32 v34, v28, v29
	v_cvt_pk_bf16_f32 v35, v30, v31
	v_cvt_pk_bf16_f32 v36, v24, v25
	v_mul_f32_e32 v29, v29, v29
	v_mul_f32_e32 v25, v25, v25
	v_fmac_f32_e32 v29, v28, v28
	v_mul_f32_e32 v28, v31, v31
	v_fmac_f32_e32 v25, v24, v24
	v_mul_f32_e32 v24, v27, v27
	s_waitcnt lgkmcnt(0)
	v_cvt_pk_bf16_f32 v37, v26, v27
	v_fmac_f32_e32 v28, v30, v30
	v_fmac_f32_e32 v24, v26, v26
	v_mul_f32_e32 v26, v21, v21
	v_mul_f32_e32 v27, v23, v23
	v_add_f32_e32 v28, v29, v28
	v_add_f32_e32 v24, v25, v24
	v_fmac_f32_e32 v26, v20, v20
	v_fmac_f32_e32 v27, v22, v22
	v_add_f32_e32 v24, v24, v28
	v_add_f32_e32 v26, v26, v27
	v_mul_f32_e32 v27, v17, v17
	v_mul_f32_e32 v28, v19, v19
	v_fmac_f32_e32 v27, v16, v16
	v_fmac_f32_e32 v28, v18, v18
	v_add_f32_e32 v27, v27, v28
	v_add_f32_e32 v27, v27, v26
	v_mov_b32_e32 v25, v24
	v_mov_b32_e32 v28, v27
	s_nop 1
	v_permlane16_swap_b32_e32 v25, v24
	v_permlane16_swap_b32_e32 v28, v27
	global_store_dwordx4 v[38:39], v[34:37], off
	v_cvt_pk_bf16_f32 v26, v20, v21
	s_waitcnt lgkmcnt(0)
	v_add_f32_e32 v20, v24, v25
	v_add_f32_e32 v24, v27, v28
	v_mov_b32_e32 v21, v20
	v_mov_b32_e32 v25, v24
	s_nop 1
	v_permlane32_swap_b32_e32 v21, v20
	v_permlane32_swap_b32_e32 v25, v24
	v_cvt_pk_bf16_f32 v27, v22, v23
	v_cvt_pk_bf16_f32 v28, v16, v17
	v_cvt_pk_bf16_f32 v29, v18, v19
	global_store_dwordx4 v[38:39], v[26:29], off offset:256
	s_and_saveexec_b64 s[0:1], vcc
	s_cbranch_execz .LBB0_901
	v_lshlrev_b64 v[16:17], 7, v[32:33]
	v_lshl_add_u64 v[16:17], s[16:17], 0, v[16:17]
	v_lshl_add_u64 v[16:17], s[30:31], 2, v[16:17]
	s_waitcnt lgkmcnt(0)
	v_add_f32_e32 v19, v20, v21
	v_lshl_add_u64 v[16:17], s[28:29], 2, v[16:17]
	v_add_f32_e32 v18, v24, v25
	global_store_dword v[16:17], v19, off
	global_store_dword v[16:17], v18, off offset:16
.LBB0_901:
	s_or_b64 exec, exec, s[0:1]
	v_add_u32_e32 v16, 0xb0, v146
	v_ashrrev_i32_e32 v17, 31, v16
	v_lshlrev_b64 v[18:19], 11, v[16:17]
	v_lshl_add_u64 v[18:19], s[14:15], 0, v[18:19]
	v_lshl_add_u64 v[18:19], s[34:35], 1, v[18:19]
	v_lshl_add_u64 v[22:23], v[144:145], 1, v[18:19]
	v_cvt_pk_bf16_f32 v18, v12, v13
	v_cvt_pk_bf16_f32 v19, v14, v15
	v_cvt_pk_bf16_f32 v20, v8, v9
	v_mul_f32_e32 v13, v13, v13
	v_mul_f32_e32 v9, v9, v9
	v_fmac_f32_e32 v13, v12, v12
	v_mul_f32_e32 v12, v15, v15
	v_fmac_f32_e32 v9, v8, v8
	v_mul_f32_e32 v8, v11, v11
	s_waitcnt lgkmcnt(0)
	v_cvt_pk_bf16_f32 v21, v10, v11
	v_fmac_f32_e32 v12, v14, v14
	v_fmac_f32_e32 v8, v10, v10
	v_mul_f32_e32 v10, v5, v5
	v_mul_f32_e32 v11, v7, v7
	v_add_f32_e32 v12, v13, v12
	v_add_f32_e32 v8, v9, v8
	v_fmac_f32_e32 v10, v4, v4
	v_fmac_f32_e32 v11, v6, v6
	v_add_f32_e32 v8, v8, v12
	v_add_f32_e32 v10, v10, v11
	v_mul_f32_e32 v11, v1, v1
	v_mul_f32_e32 v12, v3, v3
	v_fmac_f32_e32 v11, v0, v0
	v_fmac_f32_e32 v12, v2, v2
	v_add_f32_e32 v11, v11, v12
	v_add_f32_e32 v11, v11, v10
	v_mov_b32_e32 v9, v8
	v_mov_b32_e32 v12, v11
	s_nop 1
	v_permlane16_swap_b32_e32 v9, v8
	v_permlane16_swap_b32_e32 v12, v11
	global_store_dwordx4 v[22:23], v[18:21], off
	v_cvt_pk_bf16_f32 v10, v4, v5
	s_waitcnt lgkmcnt(0)
	v_add_f32_e32 v4, v8, v9
	v_add_f32_e32 v8, v11, v12
	v_mov_b32_e32 v5, v4
	v_mov_b32_e32 v9, v8
	s_nop 1
	v_permlane32_swap_b32_e32 v5, v4
	v_permlane32_swap_b32_e32 v9, v8
	v_cvt_pk_bf16_f32 v11, v6, v7
	v_cvt_pk_bf16_f32 v12, v0, v1
	v_cvt_pk_bf16_f32 v13, v2, v3
	global_store_dwordx4 v[22:23], v[10:13], off offset:256
	s_and_saveexec_b64 s[0:1], vcc
	s_cbranch_execz .LBB0_903
	v_lshlrev_b64 v[0:1], 7, v[16:17]
	v_lshl_add_u64 v[0:1], s[16:17], 0, v[0:1]
	v_lshl_add_u64 v[0:1], s[30:31], 2, v[0:1]
	s_waitcnt lgkmcnt(0)
	v_add_f32_e32 v3, v4, v5
	v_lshl_add_u64 v[0:1], s[28:29], 2, v[0:1]
	v_add_f32_e32 v2, v8, v9
	global_store_dword v[0:1], v3, off
	global_store_dword v[0:1], v2, off offset:16

; __device__ __forceinline__ unsigned cvt_pk_bf16(float lo, float hi) { unsigned r; asm volatile("v_cvt_pk_bf16_f32 %0, %1, %2" : "=v"(r) : "v"(lo), "v"(hi)); return r; }
; __device__ __forceinline__ void st8(bf16_t* p, f32x4 a, f32x4 b) { u32x4 w; w.x = cvt_pk_bf16(a[0], a[1]); w.y = cvt_pk_bf16(a[2], a[3]); w.z = cvt_pk_bf16(b[0], b[1]); w.w = cvt_pk_bf16(b[2], b[3]); *(u32x4*)p = w; }
; __device__ __forceinline__ float ssq4(f32x4 a) { return (a[0] * a[0] + a[1] * a[1]) + (a[2] * a[2] + a[3] * a[3]); }
; __device__ __forceinline__ float red_fq(float p) { p += __shfl_xor(p, 16); p += __shfl_xor(p, 32); return p; }
;     __device__ __forceinline__ void operator()(const f32x4 (&acc)[2][2][4][2], const Unit& u, int wr, int wc, int fr, int fq) const {
;     ...
;                 const int row = row0 + ai * HALF + m * 16;
;                 const f32x4 a0 = acc[ai][0][m][0], a1 = acc[ai][0][m][1], b0 = acc[ai][1][m][0], b1 = acc[ai][1][m][1];
;                 bf16_t* p = OUT + (size_t)row * 1024 + pn * 256 + cw;
;                 st8(p, a0, a1); st8(p + HALF, b0, b1);
;                 const float pa = red_fq(ssq4(a0) + ssq4(a1)), pb = red_fq(ssq4(b0) + ssq4(b1));
;                 if (fq == 0) { SSQ[(size_t)row * 32 + pn * 8 + wc] = pa; SSQ[(size_t)row * 32 + pn * 8 + 4 + wc] = pb; }
.LBB0_1475:
	v_mov_b32_e32 v145, v148
	v_mov_b32_e32 v147, v149
	s_mov_b32 s1, s41
	s_mov_b32 s6, s50
	s_lshl_b32 s0, s0, 8
	s_lshl_b32 s1, s1, 6
	s_add_i32 s1, s1, s0
	v_add_u32_e32 v146, s1, v145
	v_lshlrev_b32_e32 v144, 3, v147
	v_cmp_eq_u32_e32 vcc, 0, v147
	v_ashrrev_i32_e32 v147, 31, v146
	s_lshl_b32 s34, s59, 8
	v_lshlrev_b64 v[156:157], 11, v[146:147]
	v_lshl_add_u32 v144, s6, 5, v144
	s_ashr_i32 s35, s34, 31
	v_lshl_add_u64 v[156:157], s[10:11], 0, v[156:157]
	v_ashrrev_i32_e32 v145, 31, v144
	v_lshl_add_u64 v[156:157], s[34:35], 1, v[156:157]
	v_lshl_add_u64 v[160:161], v[144:145], 1, v[156:157]
	v_cvt_pk_bf16_f32 v156, v124, v125
	v_mul_f32_e32 v125, v125, v125
	v_fmac_f32_e32 v125, v124, v124
	v_mul_f32_e32 v124, v127, v127
	v_fmac_f32_e32 v124, v126, v126
	v_cvt_pk_bf16_f32 v157, v126, v127
	v_add_f32_e32 v124, v125, v124
	v_mul_f32_e32 v125, v121, v121
	v_mul_f32_e32 v126, v123, v123
	v_cvt_pk_bf16_f32 v158, v120, v121
	v_cvt_pk_bf16_f32 v159, v122, v123
	global_store_dwordx4 v[160:161], v[156:159], off
	v_fmac_f32_e32 v125, v120, v120
	v_fmac_f32_e32 v126, v122, v122
	v_cvt_pk_bf16_f32 v156, v116, v117
	v_mul_f32_e32 v117, v117, v117
	v_fmac_f32_e32 v117, v116, v116
	v_mul_f32_e32 v116, v119, v119
	v_add_f32_e32 v125, v125, v126
	v_and_b32_e32 v126, 64, v154
	v_fmac_f32_e32 v116, v118, v118
	v_add_f32_e32 v125, v125, v124
	v_xor_b32_e32 v124, 16, v154
	v_add_u32_e32 v126, 64, v126
	v_add_f32_e32 v116, v117, v116
	v_mul_f32_e32 v117, v113, v113
	v_mul_f32_e32 v122, v115, v115
	v_cmp_lt_i32_e64 s[0:1], v124, v126
	v_fmac_f32_e32 v117, v112, v112
	v_fmac_f32_e32 v122, v114, v114
	v_cndmask_b32_e64 v124, v154, v124, s[0:1]
	v_add_f32_e32 v117, v117, v122
	v_lshlrev_b32_e32 v124, 2, v124
	v_add_f32_e32 v122, v117, v116
	v_mov_b32_e32 v127, v125
	v_mov_b32_e32 v123, v122
	s_nop 1
	v_permlane16_swap_b32_e32 v127, v125
	v_permlane16_swap_b32_e32 v123, v122
	v_xor_b32_e32 v121, 32, v154
	v_cmp_lt_i32_e64 s[0:1], v121, v126
	s_lshl_b32 s30, s59, 3
	s_waitcnt lgkmcnt(0)
	v_add_f32_e32 v120, v125, v127
	v_cndmask_b32_e64 v116, v154, v121, s[0:1]
	v_lshlrev_b32_e32 v116, 2, v116
	v_add_f32_e32 v121, v122, v123
	v_mov_b32_e32 v117, v120
	v_mov_b32_e32 v122, v121
	s_nop 1
	v_permlane32_swap_b32_e32 v117, v120
	v_permlane32_swap_b32_e32 v122, v121
	s_ashr_i32 s31, s30, 31
	s_ashr_i32 s7, s6, 31
	v_cvt_pk_bf16_f32 v157, v118, v119
	v_cvt_pk_bf16_f32 v158, v112, v113
	v_cvt_pk_bf16_f32 v159, v114, v115
	global_store_dwordx4 v[160:161], v[156:159], off offset:256
	s_and_saveexec_b64 s[0:1], vcc
	s_cbranch_execz .LBB0_1477
	v_lshlrev_b64 v[112:113], 7, v[146:147]
	v_lshl_add_u64 v[112:113], s[18:19], 0, v[112:113]
	v_lshl_add_u64 v[112:113], s[30:31], 2, v[112:113]
	s_waitcnt lgkmcnt(0)
	v_add_f32_e32 v115, v120, v117
	v_lshl_add_u64 v[112:113], s[6:7], 2, v[112:113]
	v_add_f32_e32 v114, v121, v122
	global_store_dword v[112:113], v115, off
	global_store_dword v[112:113], v114, off offset:16

; __device__ __forceinline__ unsigned cvt_pk_bf16(float lo, float hi) { unsigned r; asm volatile("v_cvt_pk_bf16_f32 %0, %1, %2" : "=v"(r) : "v"(lo), "v"(hi)); return r; }
; __device__ __forceinline__ void st8(bf16_t* p, f32x4 a, f32x4 b) { u32x4 w; w.x = cvt_pk_bf16(a[0], a[1]); w.y = cvt_pk_bf16(a[2], a[3]); w.z = cvt_pk_bf16(b[0], b[1]); w.w = cvt_pk_bf16(b[2], b[3]); *(u32x4*)p = w; }
; __device__ __forceinline__ float ssq4(f32x4 a) { return (a[0] * a[0] + a[1] * a[1]) + (a[2] * a[2] + a[3] * a[3]); }
; __device__ __forceinline__ float red_fq(float p) { p += __shfl_xor(p, 16); p += __shfl_xor(p, 32); return p; }
;     __device__ __forceinline__ void operator()(const f32x4 (&acc)[2][2][4][2], const Unit& u, int wr, int wc, int fr, int fq) const {
;     ...
;                 const int row = row0 + ai * HALF + m * 16;
;                 const f32x4 a0 = acc[ai][0][m][0], a1 = acc[ai][0][m][1], b0 = acc[ai][1][m][0], b1 = acc[ai][1][m][1];
;                 bf16_t* p = OUT + (size_t)row * 1024 + pn * 256 + cw;
;                 st8(p, a0, a1); st8(p + HALF, b0, b1);
;                 const float pa = red_fq(ssq4(a0) + ssq4(a1)), pb = red_fq(ssq4(b0) + ssq4(b1));
;                 if (fq == 0) { SSQ[(size_t)row * 32 + pn * 8 + wc] = pa; SSQ[(size_t)row * 32 + pn * 8 + 4 + wc] = pb; }
.LBB0_1687:
	v_mov_b32_e32 v147, v149
	v_mov_b32_e32 v145, v148
	s_mov_b32 s28, s50
	s_mov_b32 s0, s41
	s_lshl_b32 s1, s34, 8
	s_lshl_b32 s0, s0, 6
	s_add_i32 s0, s0, s1
	v_add_u32_e32 v146, s0, v145
	v_lshlrev_b32_e32 v144, 3, v147
	v_cmp_eq_u32_e32 vcc, 0, v147
	v_ashrrev_i32_e32 v147, 31, v146
	s_lshl_b32 s34, s60, 8
	v_lshlrev_b64 v[156:157], 11, v[146:147]
	v_lshl_add_u32 v144, s28, 5, v144
	s_ashr_i32 s35, s34, 31
	v_lshl_add_u64 v[156:157], s[14:15], 0, v[156:157]
	v_ashrrev_i32_e32 v145, 31, v144
	v_lshl_add_u64 v[156:157], s[34:35], 1, v[156:157]
	v_lshl_add_u64 v[160:161], v[144:145], 1, v[156:157]
	v_cvt_pk_bf16_f32 v156, v124, v125
	v_mul_f32_e32 v125, v125, v125
	v_fmac_f32_e32 v125, v124, v124
	v_mul_f32_e32 v124, v127, v127
	v_fmac_f32_e32 v124, v126, v126
	v_cvt_pk_bf16_f32 v157, v126, v127
	v_add_f32_e32 v124, v125, v124
	v_mul_f32_e32 v125, v121, v121
	v_mul_f32_e32 v126, v123, v123
	v_cvt_pk_bf16_f32 v158, v120, v121
	v_cvt_pk_bf16_f32 v159, v122, v123
	global_store_dwordx4 v[160:161], v[156:159], off
	v_fmac_f32_e32 v125, v120, v120
	v_fmac_f32_e32 v126, v122, v122
	v_cvt_pk_bf16_f32 v156, v116, v117
	v_mul_f32_e32 v117, v117, v117
	v_fmac_f32_e32 v117, v116, v116
	v_mul_f32_e32 v116, v119, v119
	v_add_f32_e32 v125, v125, v126
	v_and_b32_e32 v126, 64, v154
	v_fmac_f32_e32 v116, v118, v118
	v_add_f32_e32 v125, v125, v124
	v_xor_b32_e32 v124, 16, v154
	v_add_u32_e32 v126, 64, v126
	v_add_f32_e32 v116, v117, v116
	v_mul_f32_e32 v117, v113, v113
	v_mul_f32_e32 v122, v115, v115
	v_cmp_lt_i32_e64 s[0:1], v124, v126
	v_fmac_f32_e32 v117, v112, v112
	v_fmac_f32_e32 v122, v114, v114
	v_cndmask_b32_e64 v124, v154, v124, s[0:1]
	v_add_f32_e32 v117, v117, v122
	v_lshlrev_b32_e32 v124, 2, v124
	v_add_f32_e32 v122, v117, v116
	v_mov_b32_e32 v127, v125
	v_mov_b32_e32 v123, v122
	s_nop 1
	v_permlane16_swap_b32_e32 v127, v125
	v_permlane16_swap_b32_e32 v123, v122
	v_xor_b32_e32 v121, 32, v154
	v_cmp_lt_i32_e64 s[0:1], v121, v126
	s_lshl_b32 s30, s60, 3
	s_waitcnt lgkmcnt(0)
	v_add_f32_e32 v120, v125, v127
	v_cndmask_b32_e64 v116, v154, v121, s[0:1]
	v_lshlrev_b32_e32 v116, 2, v116
	v_add_f32_e32 v121, v122, v123
	v_mov_b32_e32 v117, v120
	v_mov_b32_e32 v122, v121
	s_nop 1
	v_permlane32_swap_b32_e32 v117, v120
	v_permlane32_swap_b32_e32 v122, v121
	s_ashr_i32 s31, s30, 31
	s_ashr_i32 s29, s28, 31
	v_cvt_pk_bf16_f32 v157, v118, v119
	v_cvt_pk_bf16_f32 v158, v112, v113
	v_cvt_pk_bf16_f32 v159, v114, v115
	global_store_dwordx4 v[160:161], v[156:159], off offset:256
	s_and_saveexec_b64 s[0:1], vcc
	s_cbranch_execz .LBB0_1689
	v_lshlrev_b64 v[112:113], 7, v[146:147]
	v_lshl_add_u64 v[112:113], s[16:17], 0, v[112:113]
	v_lshl_add_u64 v[112:113], s[30:31], 2, v[112:113]
	s_waitcnt lgkmcnt(0)
	v_add_f32_e32 v115, v120, v117
	v_lshl_add_u64 v[112:113], s[28:29], 2, v[112:113]
	v_add_f32_e32 v114, v121, v122
	global_store_dword v[112:113], v115, off
	global_store_dword v[112:113], v114, off offset:16
